# all in-proj epilogue stores (and the layer-1 weight-copy stores in its tail) write-through (sc1)
# baseline (speedup 1.0000x reference)
; __device__ __forceinline__ unsigned cvt_pk_bf16(float lo, float hi) { unsigned r; asm volatile("v_cvt_pk_bf16_f32 %0, %1, %2" : "=v"(r) : "v"(lo), "v"(hi)); return r; }
; __device__ __forceinline__ float silu_f(float v) { return v * __builtin_amdgcn_rcpf(1.0f + __builtin_amdgcn_exp2f(-v * LOG2E_)); }
;     __device__ __forceinline__ void operator()(const f32x4 (&acc)[2][2][4][2], const Unit& u, int wr, int wc, int fr, int fq) const {
;     ...
;         if (u.pn < 8) {
;             const bool bz = u.pn >= 4;
;             const int col0 = (bz ? 512 + (u.pn - 4) * 128 : u.pn * 128) + wc * 32 + 8 * fq;
; #pragma unroll
;             for (int ai = 0; ai < 2; ++ai)
; #pragma unroll
;                 for (int m = 0; m < 4; ++m) {
;                     const f32x4 a0 = acc[ai][0][m][0], a1 = acc[ai][0][m][1], b0 = acc[ai][1][m][0], b1 = acc[ai][1][m][1];
;                     f32x4 v0, v1;
;                     if (bz) { v0 = (f32x4){a0[0] * silu_f(b0[0]), a0[1] * silu_f(b0[1]), a0[2] * silu_f(b0[2]), a0[3] * silu_f(b0[3])};
;                               v1 = (f32x4){a1[0] * silu_f(b1[0]), a1[1] * silu_f(b1[1]), a1[2] * silu_f(b1[2]), a1[3] * silu_f(b1[3])}; }
;                     else { v0 = a0 * b0; v1 = a1 * b1; }
;                     u32x4 w; w.x = cvt_pk_bf16(v0[0], v0[1]); w.y = cvt_pk_bf16(v0[2], v0[3]); w.z = cvt_pk_bf16(v1[0], v1[1]); w.w = cvt_pk_bf16(v1[2], v1[3]);
;                     *(u32x4*)(O + (size_t)(row0 + ai * HALF + m * 16) * PO2 + col0) = w;
;                 }
.LBB0_280:
	v_pk_mul_f32 v[116:117], v[124:125], v[116:117]
	v_lshl_or_b32 v140, s18, 7, v152
	v_pk_mul_f32 v[118:119], v[126:127], v[118:119]
	v_pk_mul_f32 v[122:123], v[122:123], v[114:115]
	v_pk_mul_f32 v[114:115], v[120:121], v[112:113]
	v_cvt_pk_bf16_f32 v112, v116, v117
	v_mov_b64_e32 v[116:117], s[74:75]
	v_ashrrev_i32_e32 v141, 31, v140
	v_cvt_pk_bf16_f32 v113, v118, v119
	v_mad_i64_i32 v[116:117], s[4:5], v155, s97, v[116:117]
	v_cndmask_b32_e64 v118, 0, 1, s[20:21]
	v_lshl_add_u64 v[116:117], v[140:141], 1, v[116:117]
	v_cmp_ne_u32_e64 s[4:5], 1, v118
	s_andn2_b64 vcc, exec, s[20:21]
	v_cvt_pk_bf16_f32 v114, v114, v115
	v_cvt_pk_bf16_f32 v115, v122, v123
	s_cmp_eq_u32 s34, 4
	s_cbranch_scc1 .Lwt3_0
	global_store_dwordx4 v[116:117], v[112:115], off sc1
	s_branch .Lwj3_0

; __device__ __forceinline__ unsigned cvt_pk_bf16(float lo, float hi) { unsigned r; asm volatile("v_cvt_pk_bf16_f32 %0, %1, %2" : "=v"(r) : "v"(lo), "v"(hi)); return r; }
; __device__ __forceinline__ float silu_f(float v) { return v * __builtin_amdgcn_rcpf(1.0f + __builtin_amdgcn_exp2f(-v * LOG2E_)); }
;     __device__ __forceinline__ void operator()(const f32x4 (&acc)[2][2][4][2], const Unit& u, int wr, int wc, int fr, int fq) const {
;     ...
;                 for (int m = 0; m < 4; ++m) {
;                     const f32x4 a0 = acc[ai][0][m][0], a1 = acc[ai][0][m][1], b0 = acc[ai][1][m][0], b1 = acc[ai][1][m][1];
;                     f32x4 v0, v1;
;                     if (bz) { v0 = (f32x4){a0[0] * silu_f(b0[0]), a0[1] * silu_f(b0[1]), a0[2] * silu_f(b0[2]), a0[3] * silu_f(b0[3])};
;                               v1 = (f32x4){a1[0] * silu_f(b1[0]), a1[1] * silu_f(b1[1]), a1[2] * silu_f(b1[2]), a1[3] * silu_f(b1[3])}; }
;                     else { v0 = a0 * b0; v1 = a1 * b1; }
;                     u32x4 w; w.x = cvt_pk_bf16(v0[0], v0[1]); w.y = cvt_pk_bf16(v0[2], v0[3]); w.z = cvt_pk_bf16(v1[0], v1[1]); w.w = cvt_pk_bf16(v1[2], v1[3]);
;                     *(u32x4*)(O + (size_t)(row0 + ai * HALF + m * 16) * PO2 + col0) = w;
;                 }
.LBB0_282:
	v_pk_mul_f32 v[102:103], v[110:111], v[102:103]
	v_pk_mul_f32 v[100:101], v[108:109], v[100:101]
	v_pk_mul_f32 v[106:107], v[106:107], v[98:99]
	v_pk_mul_f32 v[98:99], v[104:105], v[96:97]
	v_cvt_pk_bf16_f32 v96, v100, v101
	v_cvt_pk_bf16_f32 v97, v102, v103
	v_or_b32_e32 v102, 16, v155
	v_mov_b64_e32 v[100:101], s[74:75]
	v_mad_i64_i32 v[100:101], s[20:21], v102, s97, v[100:101]
	v_lshl_add_u64 v[100:101], v[140:141], 1, v[100:101]
	s_and_b64 vcc, exec, s[4:5]
	v_cvt_pk_bf16_f32 v98, v98, v99
	v_cvt_pk_bf16_f32 v99, v106, v107
	s_cmp_eq_u32 s34, 4
	s_cbranch_scc1 .Lwt3_1
	global_store_dwordx4 v[100:101], v[96:99], off sc1
	s_branch .Lwj3_1

; __device__ __forceinline__ unsigned cvt_pk_bf16(float lo, float hi) { unsigned r; asm volatile("v_cvt_pk_bf16_f32 %0, %1, %2" : "=v"(r) : "v"(lo), "v"(hi)); return r; }
; __device__ __forceinline__ float silu_f(float v) { return v * __builtin_amdgcn_rcpf(1.0f + __builtin_amdgcn_exp2f(-v * LOG2E_)); }
;     __device__ __forceinline__ void operator()(const f32x4 (&acc)[2][2][4][2], const Unit& u, int wr, int wc, int fr, int fq) const {
;     ...
;                 for (int m = 0; m < 4; ++m) {
;                     const f32x4 a0 = acc[ai][0][m][0], a1 = acc[ai][0][m][1], b0 = acc[ai][1][m][0], b1 = acc[ai][1][m][1];
;                     f32x4 v0, v1;
;                     if (bz) { v0 = (f32x4){a0[0] * silu_f(b0[0]), a0[1] * silu_f(b0[1]), a0[2] * silu_f(b0[2]), a0[3] * silu_f(b0[3])};
;                               v1 = (f32x4){a1[0] * silu_f(b1[0]), a1[1] * silu_f(b1[1]), a1[2] * silu_f(b1[2]), a1[3] * silu_f(b1[3])}; }
;                     else { v0 = a0 * b0; v1 = a1 * b1; }
;                     u32x4 w; w.x = cvt_pk_bf16(v0[0], v0[1]); w.y = cvt_pk_bf16(v0[2], v0[3]); w.z = cvt_pk_bf16(v1[0], v1[1]); w.w = cvt_pk_bf16(v1[2], v1[3]);
;                     *(u32x4*)(O + (size_t)(row0 + ai * HALF + m * 16) * PO2 + col0) = w;
;                 }
.LBB0_284:
	v_pk_mul_f32 v[86:87], v[94:95], v[86:87]
	v_pk_mul_f32 v[84:85], v[92:93], v[84:85]
	v_pk_mul_f32 v[90:91], v[90:91], v[82:83]
	v_pk_mul_f32 v[82:83], v[88:89], v[80:81]
	v_cvt_pk_bf16_f32 v80, v84, v85
	v_cvt_pk_bf16_f32 v81, v86, v87
	v_or_b32_e32 v86, 32, v155
	v_mov_b64_e32 v[84:85], s[74:75]
	v_mad_i64_i32 v[84:85], s[20:21], v86, s97, v[84:85]
	v_lshl_add_u64 v[84:85], v[140:141], 1, v[84:85]
	s_and_b64 vcc, exec, s[4:5]
	v_cvt_pk_bf16_f32 v82, v82, v83
	v_cvt_pk_bf16_f32 v83, v90, v91
	s_cmp_eq_u32 s34, 4
	s_cbranch_scc1 .Lwt3_2
	global_store_dwordx4 v[84:85], v[80:83], off sc1
	s_branch .Lwj3_2

; __device__ __forceinline__ unsigned cvt_pk_bf16(float lo, float hi) { unsigned r; asm volatile("v_cvt_pk_bf16_f32 %0, %1, %2" : "=v"(r) : "v"(lo), "v"(hi)); return r; }
; __device__ __forceinline__ float silu_f(float v) { return v * __builtin_amdgcn_rcpf(1.0f + __builtin_amdgcn_exp2f(-v * LOG2E_)); }
;     __device__ __forceinline__ void operator()(const f32x4 (&acc)[2][2][4][2], const Unit& u, int wr, int wc, int fr, int fq) const {
;     ...
;                 for (int m = 0; m < 4; ++m) {
;                     const f32x4 a0 = acc[ai][0][m][0], a1 = acc[ai][0][m][1], b0 = acc[ai][1][m][0], b1 = acc[ai][1][m][1];
;                     f32x4 v0, v1;
;                     if (bz) { v0 = (f32x4){a0[0] * silu_f(b0[0]), a0[1] * silu_f(b0[1]), a0[2] * silu_f(b0[2]), a0[3] * silu_f(b0[3])};
;                               v1 = (f32x4){a1[0] * silu_f(b1[0]), a1[1] * silu_f(b1[1]), a1[2] * silu_f(b1[2]), a1[3] * silu_f(b1[3])}; }
;                     else { v0 = a0 * b0; v1 = a1 * b1; }
;                     u32x4 w; w.x = cvt_pk_bf16(v0[0], v0[1]); w.y = cvt_pk_bf16(v0[2], v0[3]); w.z = cvt_pk_bf16(v1[0], v1[1]); w.w = cvt_pk_bf16(v1[2], v1[3]);
;                     *(u32x4*)(O + (size_t)(row0 + ai * HALF + m * 16) * PO2 + col0) = w;
;                 }
.LBB0_286:
	v_pk_mul_f32 v[70:71], v[78:79], v[70:71]
	v_pk_mul_f32 v[68:69], v[76:77], v[68:69]
	v_pk_mul_f32 v[74:75], v[74:75], v[66:67]
	v_pk_mul_f32 v[66:67], v[72:73], v[64:65]
	v_cvt_pk_bf16_f32 v64, v68, v69
	v_cvt_pk_bf16_f32 v65, v70, v71
	v_or_b32_e32 v70, 48, v155
	v_mov_b64_e32 v[68:69], s[74:75]
	v_mad_i64_i32 v[68:69], s[20:21], v70, s97, v[68:69]
	v_lshl_add_u64 v[68:69], v[140:141], 1, v[68:69]
	s_and_b64 vcc, exec, s[4:5]
	v_cvt_pk_bf16_f32 v66, v66, v67
	v_cvt_pk_bf16_f32 v67, v74, v75
	s_cmp_eq_u32 s34, 4
	s_cbranch_scc1 .Lwt3_3
	global_store_dwordx4 v[68:69], v[64:67], off sc1
	s_branch .Lwj3_3

; __device__ __forceinline__ unsigned cvt_pk_bf16(float lo, float hi) { unsigned r; asm volatile("v_cvt_pk_bf16_f32 %0, %1, %2" : "=v"(r) : "v"(lo), "v"(hi)); return r; }
; __device__ __forceinline__ float silu_f(float v) { return v * __builtin_amdgcn_rcpf(1.0f + __builtin_amdgcn_exp2f(-v * LOG2E_)); }
;     __device__ __forceinline__ void operator()(const f32x4 (&acc)[2][2][4][2], const Unit& u, int wr, int wc, int fr, int fq) const {
;     ...
;                 for (int m = 0; m < 4; ++m) {
;                     const f32x4 a0 = acc[ai][0][m][0], a1 = acc[ai][0][m][1], b0 = acc[ai][1][m][0], b1 = acc[ai][1][m][1];
;                     f32x4 v0, v1;
;                     if (bz) { v0 = (f32x4){a0[0] * silu_f(b0[0]), a0[1] * silu_f(b0[1]), a0[2] * silu_f(b0[2]), a0[3] * silu_f(b0[3])};
;                               v1 = (f32x4){a1[0] * silu_f(b1[0]), a1[1] * silu_f(b1[1]), a1[2] * silu_f(b1[2]), a1[3] * silu_f(b1[3])}; }
;                     else { v0 = a0 * b0; v1 = a1 * b1; }
;                     u32x4 w; w.x = cvt_pk_bf16(v0[0], v0[1]); w.y = cvt_pk_bf16(v0[2], v0[3]); w.z = cvt_pk_bf16(v1[0], v1[1]); w.w = cvt_pk_bf16(v1[2], v1[3]);
;                     *(u32x4*)(O + (size_t)(row0 + ai * HALF + m * 16) * PO2 + col0) = w;
;                 }
.LBB0_288:
	v_pk_mul_f32 v[52:53], v[60:61], v[52:53]
	v_add_u32_e32 v64, 0x80, v155
	v_pk_mul_f32 v[58:59], v[58:59], v[50:51]
	v_pk_mul_f32 v[50:51], v[56:57], v[48:49]
	v_cvt_pk_bf16_f32 v48, v52, v53
	v_mov_b64_e32 v[52:53], s[74:75]
	v_mad_i64_i32 v[52:53], s[20:21], v64, s97, v[52:53]
	v_lshl_add_u64 v[52:53], v[140:141], 1, v[52:53]
	s_and_b64 vcc, exec, s[4:5]
	v_pk_mul_f32 v[54:55], v[62:63], v[54:55]
	s_nop 0
	v_cvt_pk_bf16_f32 v49, v54, v55
	v_cvt_pk_bf16_f32 v50, v50, v51
	v_cvt_pk_bf16_f32 v51, v58, v59
	s_cmp_eq_u32 s34, 4
	s_cbranch_scc1 .Lwt3_4
	global_store_dwordx4 v[52:53], v[48:51], off sc1
	s_branch .Lwj3_4

; __device__ __forceinline__ unsigned cvt_pk_bf16(float lo, float hi) { unsigned r; asm volatile("v_cvt_pk_bf16_f32 %0, %1, %2" : "=v"(r) : "v"(lo), "v"(hi)); return r; }
; __device__ __forceinline__ float silu_f(float v) { return v * __builtin_amdgcn_rcpf(1.0f + __builtin_amdgcn_exp2f(-v * LOG2E_)); }
;     __device__ __forceinline__ void operator()(const f32x4 (&acc)[2][2][4][2], const Unit& u, int wr, int wc, int fr, int fq) const {
;     ...
;                 for (int m = 0; m < 4; ++m) {
;                     const f32x4 a0 = acc[ai][0][m][0], a1 = acc[ai][0][m][1], b0 = acc[ai][1][m][0], b1 = acc[ai][1][m][1];
;                     f32x4 v0, v1;
;                     if (bz) { v0 = (f32x4){a0[0] * silu_f(b0[0]), a0[1] * silu_f(b0[1]), a0[2] * silu_f(b0[2]), a0[3] * silu_f(b0[3])};
;                               v1 = (f32x4){a1[0] * silu_f(b1[0]), a1[1] * silu_f(b1[1]), a1[2] * silu_f(b1[2]), a1[3] * silu_f(b1[3])}; }
;                     else { v0 = a0 * b0; v1 = a1 * b1; }
;                     u32x4 w; w.x = cvt_pk_bf16(v0[0], v0[1]); w.y = cvt_pk_bf16(v0[2], v0[3]); w.z = cvt_pk_bf16(v1[0], v1[1]); w.w = cvt_pk_bf16(v1[2], v1[3]);
;                     *(u32x4*)(O + (size_t)(row0 + ai * HALF + m * 16) * PO2 + col0) = w;
;                 }
.LBB0_290:
	v_pk_mul_f32 v[38:39], v[46:47], v[38:39]
	v_pk_mul_f32 v[36:37], v[44:45], v[36:37]
	v_pk_mul_f32 v[42:43], v[42:43], v[34:35]
	v_pk_mul_f32 v[34:35], v[40:41], v[32:33]
	v_cvt_pk_bf16_f32 v32, v36, v37
	v_cvt_pk_bf16_f32 v33, v38, v39
	v_add_u32_e32 v38, 0x90, v155
	v_mov_b64_e32 v[36:37], s[74:75]
	v_mad_i64_i32 v[36:37], s[20:21], v38, s97, v[36:37]
	v_lshl_add_u64 v[36:37], v[140:141], 1, v[36:37]
	s_and_b64 vcc, exec, s[4:5]
	v_cvt_pk_bf16_f32 v34, v34, v35
	v_cvt_pk_bf16_f32 v35, v42, v43
	s_cmp_eq_u32 s34, 4
	s_cbranch_scc1 .Lwt3_5
	global_store_dwordx4 v[36:37], v[32:35], off sc1
	s_branch .Lwj3_5

; __device__ __forceinline__ unsigned cvt_pk_bf16(float lo, float hi) { unsigned r; asm volatile("v_cvt_pk_bf16_f32 %0, %1, %2" : "=v"(r) : "v"(lo), "v"(hi)); return r; }
; __device__ __forceinline__ float silu_f(float v) { return v * __builtin_amdgcn_rcpf(1.0f + __builtin_amdgcn_exp2f(-v * LOG2E_)); }
;     __device__ __forceinline__ void operator()(const f32x4 (&acc)[2][2][4][2], const Unit& u, int wr, int wc, int fr, int fq) const {
;     ...
;                 for (int m = 0; m < 4; ++m) {
;                     const f32x4 a0 = acc[ai][0][m][0], a1 = acc[ai][0][m][1], b0 = acc[ai][1][m][0], b1 = acc[ai][1][m][1];
;                     f32x4 v0, v1;
;                     if (bz) { v0 = (f32x4){a0[0] * silu_f(b0[0]), a0[1] * silu_f(b0[1]), a0[2] * silu_f(b0[2]), a0[3] * silu_f(b0[3])};
;                               v1 = (f32x4){a1[0] * silu_f(b1[0]), a1[1] * silu_f(b1[1]), a1[2] * silu_f(b1[2]), a1[3] * silu_f(b1[3])}; }
;                     else { v0 = a0 * b0; v1 = a1 * b1; }
;                     u32x4 w; w.x = cvt_pk_bf16(v0[0], v0[1]); w.y = cvt_pk_bf16(v0[2], v0[3]); w.z = cvt_pk_bf16(v1[0], v1[1]); w.w = cvt_pk_bf16(v1[2], v1[3]);
;                     *(u32x4*)(O + (size_t)(row0 + ai * HALF + m * 16) * PO2 + col0) = w;
;                 }
.LBB0_292:
	v_pk_mul_f32 v[22:23], v[30:31], v[22:23]
	v_pk_mul_f32 v[20:21], v[28:29], v[20:21]
	v_pk_mul_f32 v[26:27], v[26:27], v[18:19]
	v_pk_mul_f32 v[18:19], v[24:25], v[16:17]
	v_cvt_pk_bf16_f32 v16, v20, v21
	v_cvt_pk_bf16_f32 v17, v22, v23
	v_add_u32_e32 v22, 0xa0, v155
	v_mov_b64_e32 v[20:21], s[74:75]
	v_mad_i64_i32 v[20:21], s[20:21], v22, s97, v[20:21]
	v_lshl_add_u64 v[20:21], v[140:141], 1, v[20:21]
	s_and_b64 vcc, exec, s[4:5]
	v_cvt_pk_bf16_f32 v18, v18, v19
	v_cvt_pk_bf16_f32 v19, v26, v27
	s_cmp_eq_u32 s34, 4
	s_cbranch_scc1 .Lwt3_6
	global_store_dwordx4 v[20:21], v[16:19], off sc1
	s_branch .Lwj3_6

; __device__ __forceinline__ unsigned cvt_pk_bf16(float lo, float hi) { unsigned r; asm volatile("v_cvt_pk_bf16_f32 %0, %1, %2" : "=v"(r) : "v"(lo), "v"(hi)); return r; }
; __device__ __forceinline__ float silu_f(float v) { return v * __builtin_amdgcn_rcpf(1.0f + __builtin_amdgcn_exp2f(-v * LOG2E_)); }
;     __device__ __forceinline__ void operator()(const f32x4 (&acc)[2][2][4][2], const Unit& u, int wr, int wc, int fr, int fq) const {
;     ...
;                 for (int m = 0; m < 4; ++m) {
;                     const f32x4 a0 = acc[ai][0][m][0], a1 = acc[ai][0][m][1], b0 = acc[ai][1][m][0], b1 = acc[ai][1][m][1];
;                     f32x4 v0, v1;
;                     if (bz) { v0 = (f32x4){a0[0] * silu_f(b0[0]), a0[1] * silu_f(b0[1]), a0[2] * silu_f(b0[2]), a0[3] * silu_f(b0[3])};
;                               v1 = (f32x4){a1[0] * silu_f(b1[0]), a1[1] * silu_f(b1[1]), a1[2] * silu_f(b1[2]), a1[3] * silu_f(b1[3])}; }
;                     else { v0 = a0 * b0; v1 = a1 * b1; }
;                     u32x4 w; w.x = cvt_pk_bf16(v0[0], v0[1]); w.y = cvt_pk_bf16(v0[2], v0[3]); w.z = cvt_pk_bf16(v1[0], v1[1]); w.w = cvt_pk_bf16(v1[2], v1[3]);
;                     *(u32x4*)(O + (size_t)(row0 + ai * HALF + m * 16) * PO2 + col0) = w;
;                 }
.LBB0_294:
	v_pk_mul_f32 v[6:7], v[14:15], v[6:7]
	v_pk_mul_f32 v[4:5], v[12:13], v[4:5]
	v_pk_mul_f32 v[10:11], v[10:11], v[2:3]
	v_pk_mul_f32 v[2:3], v[8:9], v[0:1]
	v_cvt_pk_bf16_f32 v0, v4, v5
	v_cvt_pk_bf16_f32 v1, v6, v7
	v_add_u32_e32 v6, 0xb0, v155
	v_mov_b64_e32 v[4:5], s[74:75]
	v_mad_i64_i32 v[4:5], s[4:5], v6, s97, v[4:5]
	v_lshl_add_u64 v[4:5], v[140:141], 1, v[4:5]
	v_cvt_pk_bf16_f32 v2, v2, v3
	v_cvt_pk_bf16_f32 v3, v10, v11
	s_cmp_eq_u32 s34, 4
	s_cbranch_scc1 .Lwt3_7
	global_store_dwordx4 v[4:5], v[0:3], off sc1
	s_branch .Lwj3_7

; __device__ __forceinline__ unsigned cvt_pk_bf16(float lo, float hi) { unsigned r; asm volatile("v_cvt_pk_bf16_f32 %0, %1, %2" : "=v"(r) : "v"(lo), "v"(hi)); return r; }
; __device__ __forceinline__ float silu_f(float v) { return v * __builtin_amdgcn_rcpf(1.0f + __builtin_amdgcn_exp2f(-v * LOG2E_)); }
;     __device__ __forceinline__ void operator()(const f32x4 (&acc)[2][2][4][2], const Unit& u, int wr, int wc, int fr, int fq) const {
;     ...
;         } else {
;             const int col0 = u.pn * BM - 1024 + wc * 32 + 8 * fq;
;             const bool za = u.pn >= 11;
; #pragma unroll
;             for (int ai = 0; ai < 2; ++ai)
; #pragma unroll
;                 for (int m = 0; m < 4; ++m) { bf16_t* rowp = O + (size_t)(row0 + ai * HALF + m * 16) * PO2 + col0;
; #pragma unroll
;                     for (int bj = 0; bj < 2; ++bj) { f32x4 v0 = acc[ai][bj][m][0], v1 = acc[ai][bj][m][1];
;                         if (za) { v0 = (f32x4){silu_f(v0[0]), silu_f(v0[1]), silu_f(v0[2]), silu_f(v0[3])}; v1 = (f32x4){silu_f(v1[0]), silu_f(v1[1]), silu_f(v1[2]), silu_f(v1[3])}; }
;                         u32x4 w; w.x = cvt_pk_bf16(v0[0], v0[1]); w.y = cvt_pk_bf16(v0[2], v0[3]); w.z = cvt_pk_bf16(v1[0], v1[1]); w.w = cvt_pk_bf16(v1[2], v1[3]);
;                         *(u32x4*)(rowp + bj * HALF) = w; } }
.LBB0_298:
	v_mov_b64_e32 v[140:141], s[74:75]
	v_lshl_add_u32 v172, s18, 8, v153
	v_mad_i64_i32 v[140:141], s[4:5], v155, s97, v[140:141]
	v_lshl_add_u64 v[140:141], v[172:173], 1, v[140:141]
	v_cvt_pk_bf16_f32 v146, v146, v147
	v_cvt_pk_bf16_f32 v147, v142, v143
	v_cvt_pk_bf16_f32 v148, v148, v149
	v_cvt_pk_bf16_f32 v149, v144, v145
	v_cndmask_b32_e64 v142, 0, 1, s[20:21]
	s_cmp_eq_u32 s34, 4
	s_cbranch_scc1 .Lwt3_8
	global_store_dwordx4 v[140:141], v[146:149], off sc1
	s_branch .Lwj3_8

; __device__ __forceinline__ unsigned cvt_pk_bf16(float lo, float hi) { unsigned r; asm volatile("v_cvt_pk_bf16_f32 %0, %1, %2" : "=v"(r) : "v"(lo), "v"(hi)); return r; }
; __device__ __forceinline__ float silu_f(float v) { return v * __builtin_amdgcn_rcpf(1.0f + __builtin_amdgcn_exp2f(-v * LOG2E_)); }
;     __device__ __forceinline__ void operator()(const f32x4 (&acc)[2][2][4][2], const Unit& u, int wr, int wc, int fr, int fq) const {
;     ...
;                     for (int bj = 0; bj < 2; ++bj) { f32x4 v0 = acc[ai][bj][m][0], v1 = acc[ai][bj][m][1];
;                         if (za) { v0 = (f32x4){silu_f(v0[0]), silu_f(v0[1]), silu_f(v0[2]), silu_f(v0[3])}; v1 = (f32x4){silu_f(v1[0]), silu_f(v1[1]), silu_f(v1[2]), silu_f(v1[3])}; }
;                         u32x4 w; w.x = cvt_pk_bf16(v0[0], v0[1]); w.y = cvt_pk_bf16(v0[2], v0[3]); w.z = cvt_pk_bf16(v1[0], v1[1]); w.w = cvt_pk_bf16(v1[2], v1[3]);
;                         *(u32x4*)(rowp + bj * HALF) = w; } }
.LBB0_300:
	v_cvt_pk_bf16_f32 v146, v146, v147
	v_cvt_pk_bf16_f32 v147, v142, v143
	s_nop 0
	v_cvt_pk_bf16_f32 v148, v148, v149
	v_cvt_pk_bf16_f32 v149, v144, v145
	s_cmp_eq_u32 s34, 4
	s_cbranch_scc1 .Lwt3_9
	global_store_dwordx4 v[140:141], v[146:149], off offset:256 sc1
	s_branch .Lwj3_9

; __device__ __forceinline__ unsigned cvt_pk_bf16(float lo, float hi) { unsigned r; asm volatile("v_cvt_pk_bf16_f32 %0, %1, %2" : "=v"(r) : "v"(lo), "v"(hi)); return r; }
; __device__ __forceinline__ float silu_f(float v) { return v * __builtin_amdgcn_rcpf(1.0f + __builtin_amdgcn_exp2f(-v * LOG2E_)); }
;     __device__ __forceinline__ void operator()(const f32x4 (&acc)[2][2][4][2], const Unit& u, int wr, int wc, int fr, int fq) const {
;     ...
;                 for (int m = 0; m < 4; ++m) { bf16_t* rowp = O + (size_t)(row0 + ai * HALF + m * 16) * PO2 + col0;
; #pragma unroll
;                     for (int bj = 0; bj < 2; ++bj) { f32x4 v0 = acc[ai][bj][m][0], v1 = acc[ai][bj][m][1];
;                         if (za) { v0 = (f32x4){silu_f(v0[0]), silu_f(v0[1]), silu_f(v0[2]), silu_f(v0[3])}; v1 = (f32x4){silu_f(v1[0]), silu_f(v1[1]), silu_f(v1[2]), silu_f(v1[3])}; }
;                         u32x4 w; w.x = cvt_pk_bf16(v0[0], v0[1]); w.y = cvt_pk_bf16(v0[2], v0[3]); w.z = cvt_pk_bf16(v1[0], v1[1]); w.w = cvt_pk_bf16(v1[2], v1[3]);
;                         *(u32x4*)(rowp + bj * HALF) = w; } }
.LBB0_302:
	v_or_b32_e32 v156, 16, v155
	v_mov_b64_e32 v[140:141], s[74:75]
	v_mad_i64_i32 v[140:141], s[20:21], v156, s97, v[140:141]
	v_lshl_add_u64 v[140:141], v[172:173], 1, v[140:141]
	v_cvt_pk_bf16_f32 v146, v146, v147
	v_cvt_pk_bf16_f32 v147, v142, v143
	v_cvt_pk_bf16_f32 v148, v148, v149
	v_cvt_pk_bf16_f32 v149, v144, v145
	s_cmp_eq_u32 s34, 4
	s_cbranch_scc1 .Lwt3_10
	global_store_dwordx4 v[140:141], v[146:149], off sc1
	s_branch .Lwj3_10

; __device__ __forceinline__ unsigned cvt_pk_bf16(float lo, float hi) { unsigned r; asm volatile("v_cvt_pk_bf16_f32 %0, %1, %2" : "=v"(r) : "v"(lo), "v"(hi)); return r; }
; __device__ __forceinline__ float silu_f(float v) { return v * __builtin_amdgcn_rcpf(1.0f + __builtin_amdgcn_exp2f(-v * LOG2E_)); }
;     __device__ __forceinline__ void operator()(const f32x4 (&acc)[2][2][4][2], const Unit& u, int wr, int wc, int fr, int fq) const {
;     ...
;                 for (int m = 0; m < 4; ++m) { bf16_t* rowp = O + (size_t)(row0 + ai * HALF + m * 16) * PO2 + col0;
; #pragma unroll
;                     for (int bj = 0; bj < 2; ++bj) { f32x4 v0 = acc[ai][bj][m][0], v1 = acc[ai][bj][m][1];
;                         if (za) { v0 = (f32x4){silu_f(v0[0]), silu_f(v0[1]), silu_f(v0[2]), silu_f(v0[3])}; v1 = (f32x4){silu_f(v1[0]), silu_f(v1[1]), silu_f(v1[2]), silu_f(v1[3])}; }
;                         u32x4 w; w.x = cvt_pk_bf16(v0[0], v0[1]); w.y = cvt_pk_bf16(v0[2], v0[3]); w.z = cvt_pk_bf16(v1[0], v1[1]); w.w = cvt_pk_bf16(v1[2], v1[3]);
;                         *(u32x4*)(rowp + bj * HALF) = w; } }
.LBB0_306:
	v_or_b32_e32 v156, 32, v155
	v_mov_b64_e32 v[140:141], s[74:75]
	v_mad_i64_i32 v[140:141], s[20:21], v156, s97, v[140:141]
	v_lshl_add_u64 v[140:141], v[172:173], 1, v[140:141]
	v_cvt_pk_bf16_f32 v146, v146, v147
	v_cvt_pk_bf16_f32 v147, v142, v143
	v_cvt_pk_bf16_f32 v148, v148, v149
	v_cvt_pk_bf16_f32 v149, v144, v145
	s_cmp_eq_u32 s34, 4
	s_cbranch_scc1 .Lwt3_12
	global_store_dwordx4 v[140:141], v[146:149], off sc1
	s_branch .Lwj3_12

; __device__ __forceinline__ unsigned cvt_pk_bf16(float lo, float hi) { unsigned r; asm volatile("v_cvt_pk_bf16_f32 %0, %1, %2" : "=v"(r) : "v"(lo), "v"(hi)); return r; }
; __device__ __forceinline__ float silu_f(float v) { return v * __builtin_amdgcn_rcpf(1.0f + __builtin_amdgcn_exp2f(-v * LOG2E_)); }
;     __device__ __forceinline__ void operator()(const f32x4 (&acc)[2][2][4][2], const Unit& u, int wr, int wc, int fr, int fq) const {
;     ...
;                 for (int m = 0; m < 4; ++m) { bf16_t* rowp = O + (size_t)(row0 + ai * HALF + m * 16) * PO2 + col0;
; #pragma unroll
;                     for (int bj = 0; bj < 2; ++bj) { f32x4 v0 = acc[ai][bj][m][0], v1 = acc[ai][bj][m][1];
;                         if (za) { v0 = (f32x4){silu_f(v0[0]), silu_f(v0[1]), silu_f(v0[2]), silu_f(v0[3])}; v1 = (f32x4){silu_f(v1[0]), silu_f(v1[1]), silu_f(v1[2]), silu_f(v1[3])}; }
;                         u32x4 w; w.x = cvt_pk_bf16(v0[0], v0[1]); w.y = cvt_pk_bf16(v0[2], v0[3]); w.z = cvt_pk_bf16(v1[0], v1[1]); w.w = cvt_pk_bf16(v1[2], v1[3]);
;                         *(u32x4*)(rowp + bj * HALF) = w; } }
.LBB0_310:
	v_or_b32_e32 v156, 48, v155
	v_mov_b64_e32 v[140:141], s[74:75]
	v_mad_i64_i32 v[140:141], s[20:21], v156, s97, v[140:141]
	v_lshl_add_u64 v[140:141], v[172:173], 1, v[140:141]
	v_cvt_pk_bf16_f32 v146, v146, v147
	v_cvt_pk_bf16_f32 v147, v142, v143
	v_cvt_pk_bf16_f32 v148, v148, v149
	v_cvt_pk_bf16_f32 v149, v144, v145
	s_cmp_eq_u32 s34, 4
	s_cbranch_scc1 .Lwt3_14
	global_store_dwordx4 v[140:141], v[146:149], off sc1
	s_branch .Lwj3_14

; __device__ __forceinline__ unsigned cvt_pk_bf16(float lo, float hi) { unsigned r; asm volatile("v_cvt_pk_bf16_f32 %0, %1, %2" : "=v"(r) : "v"(lo), "v"(hi)); return r; }
; __device__ __forceinline__ float silu_f(float v) { return v * __builtin_amdgcn_rcpf(1.0f + __builtin_amdgcn_exp2f(-v * LOG2E_)); }
;     __device__ __forceinline__ void operator()(const f32x4 (&acc)[2][2][4][2], const Unit& u, int wr, int wc, int fr, int fq) const {
;     ...
;                 for (int m = 0; m < 4; ++m) { bf16_t* rowp = O + (size_t)(row0 + ai * HALF + m * 16) * PO2 + col0;
; #pragma unroll
;                     for (int bj = 0; bj < 2; ++bj) { f32x4 v0 = acc[ai][bj][m][0], v1 = acc[ai][bj][m][1];
;                         if (za) { v0 = (f32x4){silu_f(v0[0]), silu_f(v0[1]), silu_f(v0[2]), silu_f(v0[3])}; v1 = (f32x4){silu_f(v1[0]), silu_f(v1[1]), silu_f(v1[2]), silu_f(v1[3])}; }
;                         u32x4 w; w.x = cvt_pk_bf16(v0[0], v0[1]); w.y = cvt_pk_bf16(v0[2], v0[3]); w.z = cvt_pk_bf16(v1[0], v1[1]); w.w = cvt_pk_bf16(v1[2], v1[3]);
;                         *(u32x4*)(rowp + bj * HALF) = w; } }
.LBB0_314:
	v_add_u32_e32 v156, 0x80, v155
	v_mov_b64_e32 v[140:141], s[74:75]
	v_mad_i64_i32 v[140:141], s[20:21], v156, s97, v[140:141]
	v_lshl_add_u64 v[140:141], v[172:173], 1, v[140:141]
	v_cvt_pk_bf16_f32 v146, v146, v147
	v_cvt_pk_bf16_f32 v147, v142, v143
	v_cvt_pk_bf16_f32 v148, v148, v149
	v_cvt_pk_bf16_f32 v149, v144, v145
	s_cmp_eq_u32 s34, 4
	s_cbranch_scc1 .Lwt3_16
	global_store_dwordx4 v[140:141], v[146:149], off sc1
	s_branch .Lwj3_16

; __device__ __forceinline__ unsigned cvt_pk_bf16(float lo, float hi) { unsigned r; asm volatile("v_cvt_pk_bf16_f32 %0, %1, %2" : "=v"(r) : "v"(lo), "v"(hi)); return r; }
; __device__ __forceinline__ float silu_f(float v) { return v * __builtin_amdgcn_rcpf(1.0f + __builtin_amdgcn_exp2f(-v * LOG2E_)); }
;     __device__ __forceinline__ void operator()(const f32x4 (&acc)[2][2][4][2], const Unit& u, int wr, int wc, int fr, int fq) const {
;     ...
;                 for (int m = 0; m < 4; ++m) { bf16_t* rowp = O + (size_t)(row0 + ai * HALF + m * 16) * PO2 + col0;
; #pragma unroll
;                     for (int bj = 0; bj < 2; ++bj) { f32x4 v0 = acc[ai][bj][m][0], v1 = acc[ai][bj][m][1];
;                         if (za) { v0 = (f32x4){silu_f(v0[0]), silu_f(v0[1]), silu_f(v0[2]), silu_f(v0[3])}; v1 = (f32x4){silu_f(v1[0]), silu_f(v1[1]), silu_f(v1[2]), silu_f(v1[3])}; }
;                         u32x4 w; w.x = cvt_pk_bf16(v0[0], v0[1]); w.y = cvt_pk_bf16(v0[2], v0[3]); w.z = cvt_pk_bf16(v1[0], v1[1]); w.w = cvt_pk_bf16(v1[2], v1[3]);
;                         *(u32x4*)(rowp + bj * HALF) = w; } }
.LBB0_318:
	v_add_u32_e32 v156, 0x90, v155
	v_mov_b64_e32 v[140:141], s[74:75]
	v_mad_i64_i32 v[140:141], s[20:21], v156, s97, v[140:141]
	v_lshl_add_u64 v[140:141], v[172:173], 1, v[140:141]
	v_cvt_pk_bf16_f32 v146, v146, v147
	v_cvt_pk_bf16_f32 v147, v142, v143
	v_cvt_pk_bf16_f32 v148, v148, v149
	v_cvt_pk_bf16_f32 v149, v144, v145
	s_cmp_eq_u32 s34, 4
	s_cbranch_scc1 .Lwt3_18
	global_store_dwordx4 v[140:141], v[146:149], off sc1
	s_branch .Lwj3_18

; __device__ __forceinline__ unsigned cvt_pk_bf16(float lo, float hi) { unsigned r; asm volatile("v_cvt_pk_bf16_f32 %0, %1, %2" : "=v"(r) : "v"(lo), "v"(hi)); return r; }
; __device__ __forceinline__ float silu_f(float v) { return v * __builtin_amdgcn_rcpf(1.0f + __builtin_amdgcn_exp2f(-v * LOG2E_)); }
;     __device__ __forceinline__ void operator()(const f32x4 (&acc)[2][2][4][2], const Unit& u, int wr, int wc, int fr, int fq) const {
;     ...
;                 for (int m = 0; m < 4; ++m) { bf16_t* rowp = O + (size_t)(row0 + ai * HALF + m * 16) * PO2 + col0;
; #pragma unroll
;                     for (int bj = 0; bj < 2; ++bj) { f32x4 v0 = acc[ai][bj][m][0], v1 = acc[ai][bj][m][1];
;                         if (za) { v0 = (f32x4){silu_f(v0[0]), silu_f(v0[1]), silu_f(v0[2]), silu_f(v0[3])}; v1 = (f32x4){silu_f(v1[0]), silu_f(v1[1]), silu_f(v1[2]), silu_f(v1[3])}; }
;                         u32x4 w; w.x = cvt_pk_bf16(v0[0], v0[1]); w.y = cvt_pk_bf16(v0[2], v0[3]); w.z = cvt_pk_bf16(v1[0], v1[1]); w.w = cvt_pk_bf16(v1[2], v1[3]);
;                         *(u32x4*)(rowp + bj * HALF) = w; } }
.LBB0_322:
	v_add_u32_e32 v156, 0xa0, v155
	v_mov_b64_e32 v[140:141], s[74:75]
	v_mad_i64_i32 v[140:141], s[20:21], v156, s97, v[140:141]
	v_lshl_add_u64 v[140:141], v[172:173], 1, v[140:141]
	v_cvt_pk_bf16_f32 v146, v146, v147
	v_cvt_pk_bf16_f32 v147, v142, v143
	v_cvt_pk_bf16_f32 v148, v148, v149
	v_cvt_pk_bf16_f32 v149, v144, v145
	s_cmp_eq_u32 s34, 4
	s_cbranch_scc1 .Lwt3_20
	global_store_dwordx4 v[140:141], v[146:149], off sc1
	s_branch .Lwj3_20

; __device__ __forceinline__ unsigned cvt_pk_bf16(float lo, float hi) { unsigned r; asm volatile("v_cvt_pk_bf16_f32 %0, %1, %2" : "=v"(r) : "v"(lo), "v"(hi)); return r; }
; __device__ __forceinline__ float silu_f(float v) { return v * __builtin_amdgcn_rcpf(1.0f + __builtin_amdgcn_exp2f(-v * LOG2E_)); }
;     __device__ __forceinline__ void operator()(const f32x4 (&acc)[2][2][4][2], const Unit& u, int wr, int wc, int fr, int fq) const {
;     ...
;                 for (int m = 0; m < 4; ++m) { bf16_t* rowp = O + (size_t)(row0 + ai * HALF + m * 16) * PO2 + col0;
; #pragma unroll
;                     for (int bj = 0; bj < 2; ++bj) { f32x4 v0 = acc[ai][bj][m][0], v1 = acc[ai][bj][m][1];
;                         if (za) { v0 = (f32x4){silu_f(v0[0]), silu_f(v0[1]), silu_f(v0[2]), silu_f(v0[3])}; v1 = (f32x4){silu_f(v1[0]), silu_f(v1[1]), silu_f(v1[2]), silu_f(v1[3])}; }
;                         u32x4 w; w.x = cvt_pk_bf16(v0[0], v0[1]); w.y = cvt_pk_bf16(v0[2], v0[3]); w.z = cvt_pk_bf16(v1[0], v1[1]); w.w = cvt_pk_bf16(v1[2], v1[3]);
;                         *(u32x4*)(rowp + bj * HALF) = w; } }
.LBB0_326:
	v_add_u32_e32 v156, 0xb0, v155
	v_mov_b64_e32 v[140:141], s[74:75]
	v_mad_i64_i32 v[140:141], s[20:21], v156, s97, v[140:141]
	v_lshl_add_u64 v[140:141], v[172:173], 1, v[140:141]
	v_cvt_pk_bf16_f32 v146, v146, v147
	v_cvt_pk_bf16_f32 v147, v142, v143
	v_cvt_pk_bf16_f32 v148, v148, v149
	v_cvt_pk_bf16_f32 v149, v144, v145
	s_cmp_eq_u32 s34, 4
	s_cbranch_scc1 .Lwt3_22
	global_store_dwordx4 v[140:141], v[146:149], off sc1
	s_branch .Lwj3_22

; __device__ __forceinline__ unsigned cvt_pk_bf16(float lo, float hi) { unsigned r; asm volatile("v_cvt_pk_bf16_f32 %0, %1, %2" : "=v"(r) : "v"(lo), "v"(hi)); return r; }
; __device__ __forceinline__ float silu_f(float v) { return v * __builtin_amdgcn_rcpf(1.0f + __builtin_amdgcn_exp2f(-v * LOG2E_)); }
;     __device__ __forceinline__ void operator()(const f32x4 (&acc)[2][2][4][2], const Unit& u, int wr, int wc, int fr, int fq) const {
;     ...
;                     for (int bj = 0; bj < 2; ++bj) { f32x4 v0 = acc[ai][bj][m][0], v1 = acc[ai][bj][m][1];
;                         if (za) { v0 = (f32x4){silu_f(v0[0]), silu_f(v0[1]), silu_f(v0[2]), silu_f(v0[3])}; v1 = (f32x4){silu_f(v1[0]), silu_f(v1[1]), silu_f(v1[2]), silu_f(v1[3])}; }
;                         u32x4 w; w.x = cvt_pk_bf16(v0[0], v0[1]); w.y = cvt_pk_bf16(v0[2], v0[3]); w.z = cvt_pk_bf16(v1[0], v1[1]); w.w = cvt_pk_bf16(v1[2], v1[3]);
;                         *(u32x4*)(rowp + bj * HALF) = w; } }
;         }
.LBB0_328:
	v_cvt_pk_bf16_f32 v156, v148, v149
	v_cvt_pk_bf16_f32 v157, v144, v145
	s_nop 0
	v_cvt_pk_bf16_f32 v158, v146, v147
	v_cvt_pk_bf16_f32 v159, v142, v143
	s_cmp_eq_u32 s34, 4
	s_cbranch_scc1 .Lwt3_23
	global_store_dwordx4 v[140:141], v[156:159], off offset:256 sc1
	s_branch .Lwj3_23

; #define LAS __attribute__((address_space(3)))
; template <bool REMAP>
; __device__ __forceinline__ void p0_transpose_item(const float* W, int K, int N, bf16_t* WT, LAS float* scr, int item, int lane) {
;     const int nblk = N / 32, kb = item / nblk, nb = item % nblk, k0 = 64 * kb, n0 = 32 * nb;
;     const int r0 = REMAP ? win_row_of_col(n0) : n0;
; #pragma unroll
;     for (int i = 0; i < 32; ++i) { const int kk = 2 * i + (lane >> 5); scr[kk * 33 + (lane & 31)] = __builtin_nontemporal_load(W + (size_t)(k0 + kk) * N + n0 + (lane & 31)); }
;     asm volatile("s_waitcnt lgkmcnt(0)" ::: "memory");
.LBB0_338:
	s_lshl_b32 s4, s7, 6
	s_ashr_i32 s7, s6, 31
	v_lshl_add_u64 v[8:9], s[6:7], 2, v[6:7]
	v_or_b32_e32 v56, s4, v10
	s_movk_i32 s5, 0x3400
	v_mad_i64_i32 v[56:57], s[6:7], v56, s5, v[8:9]
	global_load_dword v58, v[56:57], off nt
	v_or_b32_e32 v56, s4, v11
	v_mad_i64_i32 v[56:57], s[6:7], v56, s5, v[8:9]
	global_load_dword v56, v[56:57], off nt
	v_add_lshl_u32 v172, s15, v42, 11
	s_waitcnt vmcnt(0)
	ds_write2_b32 v47, v58, v56 offset1:66
	v_or_b32_e32 v56, s4, v12
	v_mad_i64_i32 v[56:57], s[6:7], v56, s5, v[8:9]
	global_load_dword v58, v[56:57], off nt
	v_or_b32_e32 v56, s4, v13
	v_mad_i64_i32 v[56:57], s[6:7], v56, s5, v[8:9]
	global_load_dword v56, v[56:57], off nt
	s_waitcnt vmcnt(0)
	ds_write2_b32 v47, v58, v56 offset0:132 offset1:198
	v_or_b32_e32 v56, s4, v14
	v_mad_i64_i32 v[56:57], s[6:7], v56, s5, v[8:9]
	global_load_dword v58, v[56:57], off nt
	v_or_b32_e32 v56, s4, v15
	v_mad_i64_i32 v[56:57], s[6:7], v56, s5, v[8:9]
	global_load_dword v56, v[56:57], off nt
	s_waitcnt vmcnt(0)
	ds_write2_b32 v55, v58, v56 offset0:8 offset1:74
	v_or_b32_e32 v55, s4, v16
	v_mad_i64_i32 v[56:57], s[6:7], v55, s5, v[8:9]
	global_load_dword v55, v[56:57], off nt
	v_or_b32_e32 v56, s4, v17
	v_mad_i64_i32 v[56:57], s[6:7], v56, s5, v[8:9]
	global_load_dword v56, v[56:57], off nt
	s_waitcnt vmcnt(0)
	ds_write2_b32 v48, v55, v56 offset1:66
	v_or_b32_e32 v55, s4, v18
	v_mad_i64_i32 v[56:57], s[6:7], v55, s5, v[8:9]
	global_load_dword v55, v[56:57], off nt
	v_or_b32_e32 v56, s4, v19
	v_mad_i64_i32 v[56:57], s[6:7], v56, s5, v[8:9]
	global_load_dword v56, v[56:57], off nt
	s_waitcnt vmcnt(0)
	ds_write2_b32 v48, v55, v56 offset0:132 offset1:198
	v_or_b32_e32 v55, s4, v20
	v_mad_i64_i32 v[56:57], s[6:7], v55, s5, v[8:9]
	global_load_dword v55, v[56:57], off nt
	v_or_b32_e32 v56, s4, v21
	v_mad_i64_i32 v[56:57], s[6:7], v56, s5, v[8:9]
	global_load_dword v56, v[56:57], off nt
	s_waitcnt vmcnt(0)
	ds_write2_b32 v54, v55, v56 offset0:8 offset1:74
	v_or_b32_e32 v54, s4, v22
	v_mad_i64_i32 v[54:55], s[6:7], v54, s5, v[8:9]
	global_load_dword v56, v[54:55], off nt
	v_or_b32_e32 v54, s4, v23
	v_mad_i64_i32 v[54:55], s[6:7], v54, s5, v[8:9]
	global_load_dword v54, v[54:55], off nt
	s_waitcnt vmcnt(0)
	ds_write2_b32 v49, v56, v54 offset1:66
	v_or_b32_e32 v54, s4, v24
	v_mad_i64_i32 v[54:55], s[6:7], v54, s5, v[8:9]
	global_load_dword v56, v[54:55], off nt
	v_or_b32_e32 v54, s4, v25
	v_mad_i64_i32 v[54:55], s[6:7], v54, s5, v[8:9]
	global_load_dword v54, v[54:55], off nt
	s_waitcnt vmcnt(0)
	ds_write2_b32 v49, v56, v54 offset0:132 offset1:198
	v_or_b32_e32 v54, s4, v26
	v_mad_i64_i32 v[54:55], s[6:7], v54, s5, v[8:9]
	global_load_dword v56, v[54:55], off nt
	v_or_b32_e32 v54, s4, v27
	v_mad_i64_i32 v[54:55], s[6:7], v54, s5, v[8:9]
	global_load_dword v54, v[54:55], off nt
	s_waitcnt vmcnt(0)
	ds_write2_b32 v53, v56, v54 offset0:8 offset1:74
	v_or_b32_e32 v54, s4, v28
	v_mad_i64_i32 v[54:55], s[6:7], v54, s5, v[8:9]
	global_load_dword v56, v[54:55], off nt
	v_or_b32_e32 v54, s4, v29
	v_mad_i64_i32 v[54:55], s[6:7], v54, s5, v[8:9]
	global_load_dword v54, v[54:55], off nt
	s_waitcnt vmcnt(0)
	ds_write2_b32 v53, v56, v54 offset0:140 offset1:206
	v_or_b32_e32 v53, s4, v30
	v_mad_i64_i32 v[54:55], s[6:7], v53, s5, v[8:9]
	global_load_dword v53, v[54:55], off nt
	v_or_b32_e32 v54, s4, v31
	v_mad_i64_i32 v[54:55], s[6:7], v54, s5, v[8:9]
	global_load_dword v54, v[54:55], off nt
	s_waitcnt vmcnt(0)
	ds_write2_b32 v52, v53, v54 offset0:16 offset1:82
	v_or_b32_e32 v53, s4, v32
	v_mad_i64_i32 v[54:55], s[6:7], v53, s5, v[8:9]
	global_load_dword v53, v[54:55], off nt
	v_or_b32_e32 v54, s4, v33
	v_mad_i64_i32 v[54:55], s[6:7], v54, s5, v[8:9]
	global_load_dword v54, v[54:55], off nt
	s_waitcnt vmcnt(0)
	ds_write2_b32 v52, v53, v54 offset0:148 offset1:214
	v_or_b32_e32 v52, s4, v34
	v_mad_i64_i32 v[52:53], s[6:7], v52, s5, v[8:9]
	global_load_dword v54, v[52:53], off nt
	v_or_b32_e32 v52, s4, v35
	v_mad_i64_i32 v[52:53], s[6:7], v52, s5, v[8:9]
	global_load_dword v52, v[52:53], off nt
	s_waitcnt vmcnt(0)
	ds_write2_b32 v51, v54, v52 offset0:24 offset1:90
	v_or_b32_e32 v52, s4, v36
	v_mad_i64_i32 v[52:53], s[6:7], v52, s5, v[8:9]
	global_load_dword v54, v[52:53], off nt
	v_or_b32_e32 v52, s4, v37
	v_mad_i64_i32 v[52:53], s[6:7], v52, s5, v[8:9]
	global_load_dword v52, v[52:53], off nt
	s_waitcnt vmcnt(0)
	ds_write2_b32 v51, v54, v52 offset0:156 offset1:222
	v_or_b32_e32 v51, s4, v38
	v_mad_i64_i32 v[52:53], s[6:7], v51, s5, v[8:9]
	global_load_dword v51, v[52:53], off nt
	v_or_b32_e32 v52, s4, v39
	v_mad_i64_i32 v[52:53], s[6:7], v52, s5, v[8:9]
	global_load_dword v52, v[52:53], off nt
	s_waitcnt vmcnt(0)
	ds_write2_b32 v50, v51, v52 offset0:32 offset1:98
	v_or_b32_e32 v51, s4, v40
	v_mad_i64_i32 v[52:53], s[6:7], v51, s5, v[8:9]
	global_load_dword v51, v[52:53], off nt
	v_or_b32_e32 v52, s4, v41
	v_mad_i64_i32 v[8:9], s[6:7], v52, s5, v[8:9]
	global_load_dword v8, v[8:9], off nt
	s_ashr_i32 s5, s4, 31
	s_waitcnt vmcnt(0)
; #define LAS __attribute__((address_space(3)))
; __device__ __forceinline__ unsigned pk2(float lo, float hi) { return f2bf_rne(lo) | (f2bf_rne(hi) << 16); }
; template <bool REMAP>
; __device__ __forceinline__ void p0_transpose_item(const float* W, int K, int N, bf16_t* WT, LAS float* scr, int item, int lane) {
;     ...
;     const int c = lane & 7;
; #pragma unroll
;     for (int j = 0; j < 4; ++j) { const int n = (lane >> 3) + 8 * j; const LAS float* s = scr + (8 * c) * 33 + n;
;         u32x4 o; o.x = pk2(s[0 * 33], s[1 * 33]); o.y = pk2(s[2 * 33], s[3 * 33]); o.z = pk2(s[4 * 33], s[5 * 33]); o.w = pk2(s[6 * 33], s[7 * 33]);
;         *(u32x4*)(WT + (size_t)(r0 + n) * K + k0 + 8 * c) = o; }
;     asm volatile("s_waitcnt lgkmcnt(0)" ::: "memory");
	ds_write2_b32 v50, v51, v8 offset0:164 offset1:230
	s_waitcnt lgkmcnt(0)
	ds_read2_b32 v[54:55], v43 offset0:33 offset1:41
	ds_read2_b32 v[56:57], v43 offset1:8
	ds_read2_b32 v[58:59], v43 offset0:66 offset1:74
	ds_read2_b32 v[60:61], v43 offset0:99 offset1:107
	ds_read2_b32 v[62:63], v43 offset0:132 offset1:140
	ds_read2_b32 v[64:65], v43 offset0:165 offset1:173
	ds_read2_b32 v[66:67], v43 offset0:198 offset1:206
	ds_read2_b32 v[68:69], v43 offset0:231 offset1:239
	s_waitcnt lgkmcnt(7)
	v_bfe_u32 v51, v54, 16, 1
	s_waitcnt lgkmcnt(6)
	v_bfe_u32 v50, v56, 16, 1
	v_add3_u32 v50, v56, v50, s20
	v_lshrrev_b32_e32 v50, 16, v50
	v_add3_u32 v51, v54, v51, s20
	v_and_or_b32 v50, v51, s18, v50
	s_waitcnt lgkmcnt(5)
	v_bfe_u32 v51, v58, 16, 1
	v_add3_u32 v51, v58, v51, s20
	s_waitcnt lgkmcnt(4)
	v_bfe_u32 v52, v60, 16, 1
	v_lshrrev_b32_e32 v51, 16, v51
	v_add3_u32 v52, v60, v52, s20
	v_and_or_b32 v51, v52, s18, v51
	s_waitcnt lgkmcnt(3)
	v_bfe_u32 v52, v62, 16, 1
	v_add3_u32 v52, v62, v52, s20
	s_waitcnt lgkmcnt(2)
	v_bfe_u32 v53, v64, 16, 1
	v_lshrrev_b32_e32 v52, 16, v52
	v_add3_u32 v53, v64, v53, s20
	v_and_or_b32 v52, v53, s18, v52
	s_waitcnt lgkmcnt(1)
	v_bfe_u32 v53, v66, 16, 1
	v_add3_u32 v53, v66, v53, s20
	s_waitcnt lgkmcnt(0)
	v_bfe_u32 v54, v68, 16, 1
	v_lshl_add_u64 v[8:9], s[4:5], 1, v[2:3]
	v_lshrrev_b32_e32 v53, 16, v53
	v_add3_u32 v54, v68, v54, s20
	v_and_or_b32 v53, v54, s18, v53
	v_lshl_add_u64 v[70:71], v[8:9], 0, v[172:173]
	global_store_dwordx4 v[70:71], v[50:53], off sc1
	v_bfe_u32 v54, v69, 16, 1
	v_add3_u32 v54, v69, v54, s20
	v_bfe_u32 v50, v57, 16, 1
	v_add3_u32 v50, v57, v50, s20
	v_bfe_u32 v51, v55, 16, 1
	v_lshrrev_b32_e32 v50, 16, v50
	v_add3_u32 v51, v55, v51, s20
	v_and_or_b32 v50, v51, s18, v50
	v_bfe_u32 v51, v59, 16, 1
	v_add3_u32 v51, v59, v51, s20
	v_bfe_u32 v52, v61, 16, 1
	v_lshrrev_b32_e32 v51, 16, v51
	v_add3_u32 v52, v61, v52, s20
	v_and_or_b32 v51, v52, s18, v51
	v_bfe_u32 v52, v63, 16, 1
	v_add3_u32 v52, v63, v52, s20
	v_bfe_u32 v53, v65, 16, 1
	v_lshrrev_b32_e32 v52, 16, v52
	v_add3_u32 v53, v65, v53, s20
	v_and_or_b32 v52, v53, s18, v52
	v_bfe_u32 v53, v67, 16, 1
	v_add3_u32 v53, v67, v53, s20
	v_lshrrev_b32_e32 v53, 16, v53
	v_add_lshl_u32 v172, s15, v44, 11
	v_and_or_b32 v53, v54, s18, v53
	v_lshl_add_u64 v[54:55], v[8:9], 0, v[172:173]
	global_store_dwordx4 v[54:55], v[50:53], off sc1
	ds_read2_b32 v[54:55], v43 offset0:49 offset1:57
	ds_read2_b32 v[56:57], v43 offset0:16 offset1:24
	ds_read2_b32 v[58:59], v43 offset0:82 offset1:90
	ds_read2_b32 v[60:61], v43 offset0:115 offset1:123
	ds_read2_b32 v[62:63], v43 offset0:148 offset1:156
	ds_read2_b32 v[64:65], v43 offset0:181 offset1:189
	ds_read2_b32 v[66:67], v43 offset0:214 offset1:222
	ds_read2_b32 v[68:69], v43 offset0:247 offset1:255
	s_waitcnt lgkmcnt(7)
	v_bfe_u32 v51, v54, 16, 1
	s_waitcnt lgkmcnt(6)
	v_bfe_u32 v50, v56, 16, 1
	v_add3_u32 v50, v56, v50, s20
	v_lshrrev_b32_e32 v50, 16, v50
	v_add3_u32 v51, v54, v51, s20
	v_and_or_b32 v50, v51, s18, v50
	s_waitcnt lgkmcnt(5)
	v_bfe_u32 v51, v58, 16, 1
	v_add3_u32 v51, v58, v51, s20
	s_waitcnt lgkmcnt(4)
	v_bfe_u32 v52, v60, 16, 1
	v_lshrrev_b32_e32 v51, 16, v51
	v_add3_u32 v52, v60, v52, s20
	v_and_or_b32 v51, v52, s18, v51
	s_waitcnt lgkmcnt(3)
	v_bfe_u32 v52, v62, 16, 1
	v_add3_u32 v52, v62, v52, s20
	s_waitcnt lgkmcnt(2)
	v_bfe_u32 v53, v64, 16, 1
	v_lshrrev_b32_e32 v52, 16, v52
	v_add3_u32 v53, v64, v53, s20
	v_and_or_b32 v52, v53, s18, v52
	s_waitcnt lgkmcnt(1)
	v_bfe_u32 v53, v66, 16, 1
	v_add3_u32 v53, v66, v53, s20
	s_waitcnt lgkmcnt(0)
	v_bfe_u32 v54, v68, 16, 1
	v_lshrrev_b32_e32 v53, 16, v53
	v_add3_u32 v54, v68, v54, s20
	v_add_lshl_u32 v172, s15, v45, 11
	v_and_or_b32 v53, v54, s18, v53
	v_lshl_add_u64 v[70:71], v[8:9], 0, v[172:173]
	global_store_dwordx4 v[70:71], v[50:53], off sc1
	v_bfe_u32 v54, v69, 16, 1
	v_add3_u32 v54, v69, v54, s20
	v_bfe_u32 v50, v57, 16, 1
	v_add3_u32 v50, v57, v50, s20
	v_bfe_u32 v51, v55, 16, 1
	v_lshrrev_b32_e32 v50, 16, v50
	v_add3_u32 v51, v55, v51, s20
	v_and_or_b32 v50, v51, s18, v50
	v_bfe_u32 v51, v59, 16, 1
	v_add3_u32 v51, v59, v51, s20
	v_bfe_u32 v52, v61, 16, 1
	v_lshrrev_b32_e32 v51, 16, v51
	v_add3_u32 v52, v61, v52, s20
	v_and_or_b32 v51, v52, s18, v51
	v_bfe_u32 v52, v63, 16, 1
	v_add3_u32 v52, v63, v52, s20
	v_bfe_u32 v53, v65, 16, 1
	v_lshrrev_b32_e32 v52, 16, v52
	v_add3_u32 v53, v65, v53, s20
	v_and_or_b32 v52, v53, s18, v52
	v_bfe_u32 v53, v67, 16, 1
	v_add3_u32 v53, v67, v53, s20
	v_lshrrev_b32_e32 v53, 16, v53
	v_add_lshl_u32 v172, s15, v46, 11
	v_and_or_b32 v53, v54, s18, v53
	v_lshl_add_u64 v[8:9], v[8:9], 0, v[172:173]
	global_store_dwordx4 v[8:9], v[50:53], off sc1
	s_waitcnt lgkmcnt(0)

; #define LAS __attribute__((address_space(3)))
; template <bool REMAP>
; __device__ __forceinline__ void p0_transpose_item(const float* W, int K, int N, bf16_t* WT, LAS float* scr, int item, int lane) {
;     const int nblk = N / 32, kb = item / nblk, nb = item % nblk, k0 = 64 * kb, n0 = 32 * nb;
;     const int r0 = REMAP ? win_row_of_col(n0) : n0;
; #pragma unroll
;     for (int i = 0; i < 32; ++i) { const int kk = 2 * i + (lane >> 5); scr[kk * 33 + (lane & 31)] = __builtin_nontemporal_load(W + (size_t)(k0 + kk) * N + n0 + (lane & 31)); }
;     asm volatile("s_waitcnt lgkmcnt(0)" ::: "memory");
; __device__ __forceinline__ void transposes_layer(const Args& a, int l, LAS unsigned char* lds, int lane, int wave, int vrot, int nvb) {
;     ...
;     for (int it = vrot * 8 + wave; it < I_IN + I_OUT; it += nvb * 8) {
;         if (it < I_IN) p0_transpose_item<true>(a.in[10] + (size_t)l * D * PO, D, PO, WinT, scr, it, lane);
;         else p0_transpose_item<false>(a.in[15] + (size_t)l * D * D, D, D, WoutT, scr, it - I_IN, lane);
.LBB0_340:
	s_mov_b64 s[4:5], -1
	s_cmpk_gt_i32 s2, 0x67f
	v_add_u32_e32 v55, 0x400, v47
	v_add_u32_e32 v54, 0x400, v48
	v_add_u32_e32 v53, 0x400, v49
	v_add_u32_e32 v52, 0x800, v49
	v_add_u32_e32 v51, 0xc00, v49
	v_add_u32_e32 v50, 0x1000, v49
	s_cbranch_scc0 .LBB0_342
	s_add_i32 s4, s3, 0xffff3000
	s_and_b32 s5, s13, 0x3c0
	s_and_b32 s4, s4, 0x3e0
	s_lshl_b32 s86, s4, 2
	v_or_b32_e32 v56, s5, v10
	v_lshl_add_u64 v[8:9], v[4:5], 0, s[86:87]
	v_lshlrev_b32_e32 v172, 12, v56
	v_lshl_add_u64 v[56:57], v[8:9], 0, v[172:173]
	global_load_dword v58, v[56:57], off nt
	v_or_b32_e32 v56, s5, v11
	v_lshlrev_b32_e32 v172, 12, v56
	v_lshl_add_u64 v[56:57], v[8:9], 0, v[172:173]
	global_load_dword v56, v[56:57], off nt
	s_lshl_b32 s86, s5, 1
	s_waitcnt vmcnt(0)
	ds_write2_b32 v47, v58, v56 offset1:66
	v_or_b32_e32 v56, s5, v12
	v_lshlrev_b32_e32 v172, 12, v56
	v_lshl_add_u64 v[56:57], v[8:9], 0, v[172:173]
	global_load_dword v58, v[56:57], off nt
	v_or_b32_e32 v56, s5, v13
	v_lshlrev_b32_e32 v172, 12, v56
	v_lshl_add_u64 v[56:57], v[8:9], 0, v[172:173]
	global_load_dword v56, v[56:57], off nt
	s_waitcnt vmcnt(0)
	ds_write2_b32 v47, v58, v56 offset0:132 offset1:198
	v_or_b32_e32 v56, s5, v14
	v_lshlrev_b32_e32 v172, 12, v56
	v_lshl_add_u64 v[56:57], v[8:9], 0, v[172:173]
	global_load_dword v58, v[56:57], off nt
	v_or_b32_e32 v56, s5, v15
	v_lshlrev_b32_e32 v172, 12, v56
	v_lshl_add_u64 v[56:57], v[8:9], 0, v[172:173]
	global_load_dword v56, v[56:57], off nt
	s_waitcnt vmcnt(0)
	ds_write2_b32 v55, v58, v56 offset0:8 offset1:74
	v_or_b32_e32 v56, s5, v16
	v_lshlrev_b32_e32 v172, 12, v56
	v_lshl_add_u64 v[56:57], v[8:9], 0, v[172:173]
	global_load_dword v58, v[56:57], off nt
	v_or_b32_e32 v56, s5, v17
	v_lshlrev_b32_e32 v172, 12, v56
	v_lshl_add_u64 v[56:57], v[8:9], 0, v[172:173]
	global_load_dword v56, v[56:57], off nt
	s_waitcnt vmcnt(0)
	ds_write2_b32 v48, v58, v56 offset1:66
	v_or_b32_e32 v56, s5, v18
	v_lshlrev_b32_e32 v172, 12, v56
	v_lshl_add_u64 v[56:57], v[8:9], 0, v[172:173]
	global_load_dword v58, v[56:57], off nt
	v_or_b32_e32 v56, s5, v19
	v_lshlrev_b32_e32 v172, 12, v56
	v_lshl_add_u64 v[56:57], v[8:9], 0, v[172:173]
	global_load_dword v56, v[56:57], off nt
	s_waitcnt vmcnt(0)
	ds_write2_b32 v48, v58, v56 offset0:132 offset1:198
	v_or_b32_e32 v56, s5, v20
	v_lshlrev_b32_e32 v172, 12, v56
	v_lshl_add_u64 v[56:57], v[8:9], 0, v[172:173]
	global_load_dword v58, v[56:57], off nt
	v_or_b32_e32 v56, s5, v21
	v_lshlrev_b32_e32 v172, 12, v56
	v_lshl_add_u64 v[56:57], v[8:9], 0, v[172:173]
	global_load_dword v56, v[56:57], off nt
	s_waitcnt vmcnt(0)
	ds_write2_b32 v54, v58, v56 offset0:8 offset1:74
	v_or_b32_e32 v56, s5, v22
	v_lshlrev_b32_e32 v172, 12, v56
	v_lshl_add_u64 v[56:57], v[8:9], 0, v[172:173]
	global_load_dword v58, v[56:57], off nt
	v_or_b32_e32 v56, s5, v23
	v_lshlrev_b32_e32 v172, 12, v56
	v_lshl_add_u64 v[56:57], v[8:9], 0, v[172:173]
	global_load_dword v56, v[56:57], off nt
	s_waitcnt vmcnt(0)
	ds_write2_b32 v49, v58, v56 offset1:66
	v_or_b32_e32 v56, s5, v24
	v_lshlrev_b32_e32 v172, 12, v56
	v_lshl_add_u64 v[56:57], v[8:9], 0, v[172:173]
	global_load_dword v58, v[56:57], off nt
	v_or_b32_e32 v56, s5, v25
	v_lshlrev_b32_e32 v172, 12, v56
	v_lshl_add_u64 v[56:57], v[8:9], 0, v[172:173]
	global_load_dword v56, v[56:57], off nt
	s_waitcnt vmcnt(0)
	ds_write2_b32 v49, v58, v56 offset0:132 offset1:198
	v_or_b32_e32 v56, s5, v26
	v_lshlrev_b32_e32 v172, 12, v56
	v_lshl_add_u64 v[56:57], v[8:9], 0, v[172:173]
	global_load_dword v58, v[56:57], off nt
	v_or_b32_e32 v56, s5, v27
	v_lshlrev_b32_e32 v172, 12, v56
	v_lshl_add_u64 v[56:57], v[8:9], 0, v[172:173]
	global_load_dword v56, v[56:57], off nt
	s_waitcnt vmcnt(0)
	ds_write2_b32 v53, v58, v56 offset0:8 offset1:74
	v_or_b32_e32 v56, s5, v28
	v_lshlrev_b32_e32 v172, 12, v56
	v_lshl_add_u64 v[56:57], v[8:9], 0, v[172:173]
	global_load_dword v58, v[56:57], off nt
	v_or_b32_e32 v56, s5, v29
	v_lshlrev_b32_e32 v172, 12, v56
	v_lshl_add_u64 v[56:57], v[8:9], 0, v[172:173]
	global_load_dword v56, v[56:57], off nt
	s_waitcnt vmcnt(0)
	ds_write2_b32 v53, v58, v56 offset0:140 offset1:206
	v_or_b32_e32 v56, s5, v30
	v_lshlrev_b32_e32 v172, 12, v56
	v_lshl_add_u64 v[56:57], v[8:9], 0, v[172:173]
	global_load_dword v58, v[56:57], off nt
	v_or_b32_e32 v56, s5, v31
	v_lshlrev_b32_e32 v172, 12, v56
	v_lshl_add_u64 v[56:57], v[8:9], 0, v[172:173]
	global_load_dword v56, v[56:57], off nt
	s_waitcnt vmcnt(0)
	ds_write2_b32 v52, v58, v56 offset0:16 offset1:82
	v_or_b32_e32 v56, s5, v32
	v_lshlrev_b32_e32 v172, 12, v56
	v_lshl_add_u64 v[56:57], v[8:9], 0, v[172:173]
	global_load_dword v58, v[56:57], off nt
	v_or_b32_e32 v56, s5, v33
	v_lshlrev_b32_e32 v172, 12, v56
	v_lshl_add_u64 v[56:57], v[8:9], 0, v[172:173]
	global_load_dword v56, v[56:57], off nt
	s_waitcnt vmcnt(0)
	ds_write2_b32 v52, v58, v56 offset0:148 offset1:214
	v_or_b32_e32 v56, s5, v34
	v_lshlrev_b32_e32 v172, 12, v56
	v_lshl_add_u64 v[56:57], v[8:9], 0, v[172:173]
	global_load_dword v58, v[56:57], off nt
	v_or_b32_e32 v56, s5, v35
	v_lshlrev_b32_e32 v172, 12, v56
	v_lshl_add_u64 v[56:57], v[8:9], 0, v[172:173]
	global_load_dword v56, v[56:57], off nt
	s_waitcnt vmcnt(0)
	ds_write2_b32 v51, v58, v56 offset0:24 offset1:90
	v_or_b32_e32 v56, s5, v36
	v_lshlrev_b32_e32 v172, 12, v56
	v_lshl_add_u64 v[56:57], v[8:9], 0, v[172:173]
	global_load_dword v58, v[56:57], off nt
	v_or_b32_e32 v56, s5, v37
	v_lshlrev_b32_e32 v172, 12, v56
	v_lshl_add_u64 v[56:57], v[8:9], 0, v[172:173]
	global_load_dword v56, v[56:57], off nt
	s_waitcnt vmcnt(0)
; #define LAS __attribute__((address_space(3)))
; __device__ __forceinline__ unsigned pk2(float lo, float hi) { return f2bf_rne(lo) | (f2bf_rne(hi) << 16); }
; template <bool REMAP>
; __device__ __forceinline__ void p0_transpose_item(const float* W, int K, int N, bf16_t* WT, LAS float* scr, int item, int lane) {
;     ...
; #pragma unroll
;     for (int i = 0; i < 32; ++i) { const int kk = 2 * i + (lane >> 5); scr[kk * 33 + (lane & 31)] = __builtin_nontemporal_load(W + (size_t)(k0 + kk) * N + n0 + (lane & 31)); }
;     asm volatile("s_waitcnt lgkmcnt(0)" ::: "memory");
;     const int c = lane & 7;
; #pragma unroll
;     for (int j = 0; j < 4; ++j) { const int n = (lane >> 3) + 8 * j; const LAS float* s = scr + (8 * c) * 33 + n;
;         u32x4 o; o.x = pk2(s[0 * 33], s[1 * 33]); o.y = pk2(s[2 * 33], s[3 * 33]); o.z = pk2(s[4 * 33], s[5 * 33]); o.w = pk2(s[6 * 33], s[7 * 33]);
;         *(u32x4*)(WT + (size_t)(r0 + n) * K + k0 + 8 * c) = o; }
;     asm volatile("s_waitcnt lgkmcnt(0)" ::: "memory");
	ds_write2_b32 v51, v58, v56 offset0:156 offset1:222
	v_or_b32_e32 v56, s5, v38
	v_lshlrev_b32_e32 v172, 12, v56
	v_lshl_add_u64 v[56:57], v[8:9], 0, v[172:173]
	global_load_dword v58, v[56:57], off nt
	v_or_b32_e32 v56, s5, v39
	v_lshlrev_b32_e32 v172, 12, v56
	v_lshl_add_u64 v[56:57], v[8:9], 0, v[172:173]
	global_load_dword v56, v[56:57], off nt
	s_waitcnt vmcnt(0)
	ds_write2_b32 v50, v58, v56 offset0:32 offset1:98
	v_or_b32_e32 v56, s5, v40
	v_lshlrev_b32_e32 v172, 12, v56
	v_lshl_add_u64 v[56:57], v[8:9], 0, v[172:173]
	global_load_dword v56, v[56:57], off nt
	v_or_b32_e32 v57, s5, v41
	v_lshlrev_b32_e32 v172, 12, v57
	v_lshl_add_u64 v[8:9], v[8:9], 0, v[172:173]
	global_load_dword v8, v[8:9], off nt
	s_waitcnt vmcnt(0)
	ds_write2_b32 v50, v56, v8 offset0:164 offset1:230
	s_waitcnt lgkmcnt(0)
	ds_read2_b32 v[60:61], v43 offset0:33 offset1:41
	ds_read2_b32 v[62:63], v43 offset1:8
	ds_read2_b32 v[64:65], v43 offset0:66 offset1:74
	ds_read2_b32 v[66:67], v43 offset0:99 offset1:107
	ds_read2_b32 v[68:69], v43 offset0:132 offset1:140
	ds_read2_b32 v[70:71], v43 offset0:165 offset1:173
	ds_read2_b32 v[72:73], v43 offset0:198 offset1:206
	ds_read2_b32 v[74:75], v43 offset0:231 offset1:239
	s_waitcnt lgkmcnt(7)
	v_bfe_u32 v57, v60, 16, 1
	s_waitcnt lgkmcnt(6)
	v_bfe_u32 v56, v62, 16, 1
	v_add3_u32 v56, v62, v56, s20
	v_lshrrev_b32_e32 v56, 16, v56
	v_add3_u32 v57, v60, v57, s20
	v_and_or_b32 v56, v57, s18, v56
	s_waitcnt lgkmcnt(5)
	v_bfe_u32 v57, v64, 16, 1
	v_add3_u32 v57, v64, v57, s20
	s_waitcnt lgkmcnt(4)
	v_bfe_u32 v58, v66, 16, 1
	v_lshrrev_b32_e32 v57, 16, v57
	v_add3_u32 v58, v66, v58, s20
	v_and_or_b32 v57, v58, s18, v57
	s_waitcnt lgkmcnt(3)
	v_bfe_u32 v58, v68, 16, 1
	v_add3_u32 v58, v68, v58, s20
	s_waitcnt lgkmcnt(2)
	v_bfe_u32 v59, v70, 16, 1
	v_lshrrev_b32_e32 v58, 16, v58
	v_add3_u32 v59, v70, v59, s20
	v_and_or_b32 v58, v59, s18, v58
	s_waitcnt lgkmcnt(1)
	v_bfe_u32 v59, v72, 16, 1
	v_add3_u32 v59, v72, v59, s20
	s_waitcnt lgkmcnt(0)
	v_bfe_u32 v60, v74, 16, 1
	v_lshrrev_b32_e32 v59, 16, v59
	v_add3_u32 v60, v74, v60, s20
	v_and_or_b32 v59, v60, s18, v59
	v_or_b32_e32 v60, s4, v42
	v_lshl_add_u64 v[8:9], v[0:1], 0, s[86:87]
	v_lshlrev_b32_e32 v172, 11, v60
	v_lshl_add_u64 v[76:77], v[8:9], 0, v[172:173]
	global_store_dwordx4 v[76:77], v[56:59], off sc1
	v_bfe_u32 v60, v75, 16, 1
	v_add3_u32 v60, v75, v60, s20
	v_bfe_u32 v56, v63, 16, 1
	v_add3_u32 v56, v63, v56, s20
	v_bfe_u32 v57, v61, 16, 1
	v_lshrrev_b32_e32 v56, 16, v56
	v_add3_u32 v57, v61, v57, s20
	v_and_or_b32 v56, v57, s18, v56
	v_bfe_u32 v57, v65, 16, 1
	v_add3_u32 v57, v65, v57, s20
	v_bfe_u32 v58, v67, 16, 1
	v_lshrrev_b32_e32 v57, 16, v57
	v_add3_u32 v58, v67, v58, s20
	v_and_or_b32 v57, v58, s18, v57
	v_bfe_u32 v58, v69, 16, 1
	v_add3_u32 v58, v69, v58, s20
	v_bfe_u32 v59, v71, 16, 1
	v_lshrrev_b32_e32 v58, 16, v58
	v_add3_u32 v59, v71, v59, s20
	v_and_or_b32 v58, v59, s18, v58
	v_bfe_u32 v59, v73, 16, 1
	v_add3_u32 v59, v73, v59, s20
	v_lshrrev_b32_e32 v59, 16, v59
	v_and_or_b32 v59, v60, s18, v59
	v_or_b32_e32 v60, s4, v44
	v_lshlrev_b32_e32 v172, 11, v60
	v_lshl_add_u64 v[60:61], v[8:9], 0, v[172:173]
	global_store_dwordx4 v[60:61], v[56:59], off sc1
	ds_read2_b32 v[60:61], v43 offset0:49 offset1:57
	ds_read2_b32 v[62:63], v43 offset0:16 offset1:24
	ds_read2_b32 v[64:65], v43 offset0:82 offset1:90
	ds_read2_b32 v[66:67], v43 offset0:115 offset1:123
	ds_read2_b32 v[68:69], v43 offset0:148 offset1:156
	ds_read2_b32 v[70:71], v43 offset0:181 offset1:189
	ds_read2_b32 v[72:73], v43 offset0:214 offset1:222
	ds_read2_b32 v[74:75], v43 offset0:247 offset1:255
	s_waitcnt lgkmcnt(7)
	v_bfe_u32 v57, v60, 16, 1
	s_waitcnt lgkmcnt(6)
	v_bfe_u32 v56, v62, 16, 1
	v_add3_u32 v56, v62, v56, s20
	v_lshrrev_b32_e32 v56, 16, v56
	v_add3_u32 v57, v60, v57, s20
	v_and_or_b32 v56, v57, s18, v56
	s_waitcnt lgkmcnt(5)
	v_bfe_u32 v57, v64, 16, 1
	v_add3_u32 v57, v64, v57, s20
	s_waitcnt lgkmcnt(4)
	v_bfe_u32 v58, v66, 16, 1
	v_lshrrev_b32_e32 v57, 16, v57
	v_add3_u32 v58, v66, v58, s20
	v_and_or_b32 v57, v58, s18, v57
	s_waitcnt lgkmcnt(3)
	v_bfe_u32 v58, v68, 16, 1
	v_add3_u32 v58, v68, v58, s20
	s_waitcnt lgkmcnt(2)
	v_bfe_u32 v59, v70, 16, 1
	v_lshrrev_b32_e32 v58, 16, v58
	v_add3_u32 v59, v70, v59, s20
	v_and_or_b32 v58, v59, s18, v58
	s_waitcnt lgkmcnt(1)
	v_bfe_u32 v59, v72, 16, 1
	v_add3_u32 v59, v72, v59, s20
	s_waitcnt lgkmcnt(0)
	v_bfe_u32 v60, v74, 16, 1
	v_lshrrev_b32_e32 v59, 16, v59
	v_add3_u32 v60, v74, v60, s20
	v_and_or_b32 v59, v60, s18, v59
	v_or_b32_e32 v60, s4, v45
	v_lshlrev_b32_e32 v172, 11, v60
	v_lshl_add_u64 v[76:77], v[8:9], 0, v[172:173]
	global_store_dwordx4 v[76:77], v[56:59], off sc1
	v_bfe_u32 v60, v75, 16, 1
	v_add3_u32 v60, v75, v60, s20
	v_bfe_u32 v56, v63, 16, 1
	v_add3_u32 v56, v63, v56, s20
	v_bfe_u32 v57, v61, 16, 1
	v_lshrrev_b32_e32 v56, 16, v56
	v_add3_u32 v57, v61, v57, s20
	v_and_or_b32 v56, v57, s18, v56
	v_bfe_u32 v57, v65, 16, 1
	v_add3_u32 v57, v65, v57, s20
	v_bfe_u32 v58, v67, 16, 1
	v_lshrrev_b32_e32 v57, 16, v57
	v_add3_u32 v58, v67, v58, s20
	v_and_or_b32 v57, v58, s18, v57
	v_bfe_u32 v58, v69, 16, 1
	v_add3_u32 v58, v69, v58, s20
	v_bfe_u32 v59, v71, 16, 1
	v_lshrrev_b32_e32 v58, 16, v58
	v_add3_u32 v59, v71, v59, s20
	v_and_or_b32 v58, v59, s18, v58
	v_bfe_u32 v59, v73, 16, 1
	v_add3_u32 v59, v73, v59, s20
	v_lshrrev_b32_e32 v59, 16, v59
	v_and_or_b32 v59, v60, s18, v59
	v_or_b32_e32 v60, s4, v46
	v_lshlrev_b32_e32 v172, 11, v60
	v_lshl_add_u64 v[8:9], v[8:9], 0, v[172:173]
	global_store_dwordx4 v[8:9], v[56:59], off sc1
	s_waitcnt lgkmcnt(0)
	s_mov_b64 s[4:5], 0

; #define LAS __attribute__((address_space(3)))
; template <bool REMAP>
; __device__ __forceinline__ void p0_transpose_item(const float* W, int K, int N, bf16_t* WT, LAS float* scr, int item, int lane) {
;     const int nblk = N / 32, kb = item / nblk, nb = item % nblk, k0 = 64 * kb, n0 = 32 * nb;
;     const int r0 = REMAP ? win_row_of_col(n0) : n0;
; #pragma unroll
;     for (int i = 0; i < 32; ++i) { const int kk = 2 * i + (lane >> 5); scr[kk * 33 + (lane & 31)] = __builtin_nontemporal_load(W + (size_t)(k0 + kk) * N + n0 + (lane & 31)); }
;     asm volatile("s_waitcnt lgkmcnt(0)" ::: "memory");
.LBB0_362:
	s_lshl_b32 s0, s5, 6
	s_ashr_i32 s5, s4, 31
	v_lshl_add_u64 v[8:9], s[4:5], 2, v[6:7]
	v_or_b32_e32 v56, s0, v10
	s_movk_i32 s1, 0x3400
	v_mad_i64_i32 v[56:57], s[4:5], v56, s1, v[8:9]
	global_load_dword v58, v[56:57], off nt
	v_or_b32_e32 v56, s0, v11
	v_mad_i64_i32 v[56:57], s[4:5], v56, s1, v[8:9]
	global_load_dword v56, v[56:57], off nt
	v_add_lshl_u32 v172, s11, v42, 11
	s_waitcnt vmcnt(0)
	ds_write2_b32 v47, v58, v56 offset1:66
	v_or_b32_e32 v56, s0, v12
	v_mad_i64_i32 v[56:57], s[4:5], v56, s1, v[8:9]
	global_load_dword v58, v[56:57], off nt
	v_or_b32_e32 v56, s0, v13
	v_mad_i64_i32 v[56:57], s[4:5], v56, s1, v[8:9]
	global_load_dword v56, v[56:57], off nt
	s_waitcnt vmcnt(0)
	ds_write2_b32 v47, v58, v56 offset0:132 offset1:198
	v_or_b32_e32 v56, s0, v14
	v_mad_i64_i32 v[56:57], s[4:5], v56, s1, v[8:9]
	global_load_dword v58, v[56:57], off nt
	v_or_b32_e32 v56, s0, v15
	v_mad_i64_i32 v[56:57], s[4:5], v56, s1, v[8:9]
	global_load_dword v56, v[56:57], off nt
	s_waitcnt vmcnt(0)
	ds_write2_b32 v55, v58, v56 offset0:8 offset1:74
	v_or_b32_e32 v55, s0, v16
	v_mad_i64_i32 v[56:57], s[4:5], v55, s1, v[8:9]
	global_load_dword v55, v[56:57], off nt
	v_or_b32_e32 v56, s0, v17
	v_mad_i64_i32 v[56:57], s[4:5], v56, s1, v[8:9]
	global_load_dword v56, v[56:57], off nt
	s_waitcnt vmcnt(0)
	ds_write2_b32 v48, v55, v56 offset1:66
	v_or_b32_e32 v55, s0, v18
	v_mad_i64_i32 v[56:57], s[4:5], v55, s1, v[8:9]
	global_load_dword v55, v[56:57], off nt
	v_or_b32_e32 v56, s0, v19
	v_mad_i64_i32 v[56:57], s[4:5], v56, s1, v[8:9]
	global_load_dword v56, v[56:57], off nt
	s_waitcnt vmcnt(0)
	ds_write2_b32 v48, v55, v56 offset0:132 offset1:198
	v_or_b32_e32 v55, s0, v20
	v_mad_i64_i32 v[56:57], s[4:5], v55, s1, v[8:9]
	global_load_dword v55, v[56:57], off nt
	v_or_b32_e32 v56, s0, v21
	v_mad_i64_i32 v[56:57], s[4:5], v56, s1, v[8:9]
	global_load_dword v56, v[56:57], off nt
	s_waitcnt vmcnt(0)
	ds_write2_b32 v54, v55, v56 offset0:8 offset1:74
	v_or_b32_e32 v54, s0, v22
	v_mad_i64_i32 v[54:55], s[4:5], v54, s1, v[8:9]
	global_load_dword v56, v[54:55], off nt
	v_or_b32_e32 v54, s0, v23
	v_mad_i64_i32 v[54:55], s[4:5], v54, s1, v[8:9]
	global_load_dword v54, v[54:55], off nt
	s_waitcnt vmcnt(0)
	ds_write2_b32 v49, v56, v54 offset1:66
	v_or_b32_e32 v54, s0, v24
	v_mad_i64_i32 v[54:55], s[4:5], v54, s1, v[8:9]
	global_load_dword v56, v[54:55], off nt
	v_or_b32_e32 v54, s0, v25
	v_mad_i64_i32 v[54:55], s[4:5], v54, s1, v[8:9]
	global_load_dword v54, v[54:55], off nt
	s_waitcnt vmcnt(0)
	ds_write2_b32 v49, v56, v54 offset0:132 offset1:198
	v_or_b32_e32 v54, s0, v26
	v_mad_i64_i32 v[54:55], s[4:5], v54, s1, v[8:9]
	global_load_dword v56, v[54:55], off nt
	v_or_b32_e32 v54, s0, v27
	v_mad_i64_i32 v[54:55], s[4:5], v54, s1, v[8:9]
	global_load_dword v54, v[54:55], off nt
	s_waitcnt vmcnt(0)
	ds_write2_b32 v53, v56, v54 offset0:8 offset1:74
	v_or_b32_e32 v54, s0, v28
	v_mad_i64_i32 v[54:55], s[4:5], v54, s1, v[8:9]
	global_load_dword v56, v[54:55], off nt
	v_or_b32_e32 v54, s0, v29
	v_mad_i64_i32 v[54:55], s[4:5], v54, s1, v[8:9]
	global_load_dword v54, v[54:55], off nt
	s_waitcnt vmcnt(0)
	ds_write2_b32 v53, v56, v54 offset0:140 offset1:206
	v_or_b32_e32 v53, s0, v30
	v_mad_i64_i32 v[54:55], s[4:5], v53, s1, v[8:9]
	global_load_dword v53, v[54:55], off nt
	v_or_b32_e32 v54, s0, v31
	v_mad_i64_i32 v[54:55], s[4:5], v54, s1, v[8:9]
	global_load_dword v54, v[54:55], off nt
	s_waitcnt vmcnt(0)
	ds_write2_b32 v52, v53, v54 offset0:16 offset1:82
	v_or_b32_e32 v53, s0, v32
	v_mad_i64_i32 v[54:55], s[4:5], v53, s1, v[8:9]
	global_load_dword v53, v[54:55], off nt
	v_or_b32_e32 v54, s0, v33
	v_mad_i64_i32 v[54:55], s[4:5], v54, s1, v[8:9]
	global_load_dword v54, v[54:55], off nt
	s_waitcnt vmcnt(0)
	ds_write2_b32 v52, v53, v54 offset0:148 offset1:214
	v_or_b32_e32 v52, s0, v34
	v_mad_i64_i32 v[52:53], s[4:5], v52, s1, v[8:9]
	global_load_dword v54, v[52:53], off nt
	v_or_b32_e32 v52, s0, v35
	v_mad_i64_i32 v[52:53], s[4:5], v52, s1, v[8:9]
	global_load_dword v52, v[52:53], off nt
	s_waitcnt vmcnt(0)
	ds_write2_b32 v51, v54, v52 offset0:24 offset1:90
	v_or_b32_e32 v52, s0, v36
	v_mad_i64_i32 v[52:53], s[4:5], v52, s1, v[8:9]
	global_load_dword v54, v[52:53], off nt
	v_or_b32_e32 v52, s0, v37
	v_mad_i64_i32 v[52:53], s[4:5], v52, s1, v[8:9]
	global_load_dword v52, v[52:53], off nt
	s_waitcnt vmcnt(0)
	ds_write2_b32 v51, v54, v52 offset0:156 offset1:222
	v_or_b32_e32 v51, s0, v38
	v_mad_i64_i32 v[52:53], s[4:5], v51, s1, v[8:9]
	global_load_dword v51, v[52:53], off nt
	v_or_b32_e32 v52, s0, v39
	v_mad_i64_i32 v[52:53], s[4:5], v52, s1, v[8:9]
	global_load_dword v52, v[52:53], off nt
	s_waitcnt vmcnt(0)
	ds_write2_b32 v50, v51, v52 offset0:32 offset1:98
	v_or_b32_e32 v51, s0, v40
	v_mad_i64_i32 v[52:53], s[4:5], v51, s1, v[8:9]
	global_load_dword v51, v[52:53], off nt
	v_or_b32_e32 v52, s0, v41
	v_mad_i64_i32 v[8:9], s[4:5], v52, s1, v[8:9]
	global_load_dword v8, v[8:9], off nt
	s_ashr_i32 s1, s0, 31
	s_waitcnt vmcnt(0)
; #define LAS __attribute__((address_space(3)))
; __device__ __forceinline__ unsigned pk2(float lo, float hi) { return f2bf_rne(lo) | (f2bf_rne(hi) << 16); }
; template <bool REMAP>
; __device__ __forceinline__ void p0_transpose_item(const float* W, int K, int N, bf16_t* WT, LAS float* scr, int item, int lane) {
;     ...
;     const int c = lane & 7;
; #pragma unroll
;     for (int j = 0; j < 4; ++j) { const int n = (lane >> 3) + 8 * j; const LAS float* s = scr + (8 * c) * 33 + n;
;         u32x4 o; o.x = pk2(s[0 * 33], s[1 * 33]); o.y = pk2(s[2 * 33], s[3 * 33]); o.z = pk2(s[4 * 33], s[5 * 33]); o.w = pk2(s[6 * 33], s[7 * 33]);
;         *(u32x4*)(WT + (size_t)(r0 + n) * K + k0 + 8 * c) = o; }
;     asm volatile("s_waitcnt lgkmcnt(0)" ::: "memory");
	ds_write2_b32 v50, v51, v8 offset0:164 offset1:230
	s_waitcnt lgkmcnt(0)
	ds_read2_b32 v[54:55], v43 offset0:33 offset1:41
	ds_read2_b32 v[56:57], v43 offset1:8
	ds_read2_b32 v[58:59], v43 offset0:66 offset1:74
	ds_read2_b32 v[60:61], v43 offset0:99 offset1:107
	ds_read2_b32 v[62:63], v43 offset0:132 offset1:140
	ds_read2_b32 v[64:65], v43 offset0:165 offset1:173
	ds_read2_b32 v[66:67], v43 offset0:198 offset1:206
	ds_read2_b32 v[68:69], v43 offset0:231 offset1:239
	s_waitcnt lgkmcnt(7)
	v_bfe_u32 v51, v54, 16, 1
	s_waitcnt lgkmcnt(6)
	v_bfe_u32 v50, v56, 16, 1
	v_add3_u32 v50, v56, v50, s20
	v_lshrrev_b32_e32 v50, 16, v50
	v_add3_u32 v51, v54, v51, s20
	v_and_or_b32 v50, v51, s18, v50
	s_waitcnt lgkmcnt(5)
	v_bfe_u32 v51, v58, 16, 1
	v_add3_u32 v51, v58, v51, s20
	s_waitcnt lgkmcnt(4)
	v_bfe_u32 v52, v60, 16, 1
	v_lshrrev_b32_e32 v51, 16, v51
	v_add3_u32 v52, v60, v52, s20
	v_and_or_b32 v51, v52, s18, v51
	s_waitcnt lgkmcnt(3)
	v_bfe_u32 v52, v62, 16, 1
	v_add3_u32 v52, v62, v52, s20
	s_waitcnt lgkmcnt(2)
	v_bfe_u32 v53, v64, 16, 1
	v_lshrrev_b32_e32 v52, 16, v52
	v_add3_u32 v53, v64, v53, s20
	v_and_or_b32 v52, v53, s18, v52
	s_waitcnt lgkmcnt(1)
	v_bfe_u32 v53, v66, 16, 1
	v_add3_u32 v53, v66, v53, s20
	s_waitcnt lgkmcnt(0)
	v_bfe_u32 v54, v68, 16, 1
	v_lshl_add_u64 v[8:9], s[0:1], 1, v[2:3]
	v_lshrrev_b32_e32 v53, 16, v53
	v_add3_u32 v54, v68, v54, s20
	v_and_or_b32 v53, v54, s18, v53
	v_lshl_add_u64 v[70:71], v[8:9], 0, v[172:173]
	global_store_dwordx4 v[70:71], v[50:53], off sc1
	v_bfe_u32 v54, v69, 16, 1
	v_add3_u32 v54, v69, v54, s20
	v_bfe_u32 v50, v57, 16, 1
	v_add3_u32 v50, v57, v50, s20
	v_bfe_u32 v51, v55, 16, 1
	v_lshrrev_b32_e32 v50, 16, v50
	v_add3_u32 v51, v55, v51, s20
	v_and_or_b32 v50, v51, s18, v50
	v_bfe_u32 v51, v59, 16, 1
	v_add3_u32 v51, v59, v51, s20
	v_bfe_u32 v52, v61, 16, 1
	v_lshrrev_b32_e32 v51, 16, v51
	v_add3_u32 v52, v61, v52, s20
	v_and_or_b32 v51, v52, s18, v51
	v_bfe_u32 v52, v63, 16, 1
	v_add3_u32 v52, v63, v52, s20
	v_bfe_u32 v53, v65, 16, 1
	v_lshrrev_b32_e32 v52, 16, v52
	v_add3_u32 v53, v65, v53, s20
	v_and_or_b32 v52, v53, s18, v52
	v_bfe_u32 v53, v67, 16, 1
	v_add3_u32 v53, v67, v53, s20
	v_lshrrev_b32_e32 v53, 16, v53
	v_add_lshl_u32 v172, s11, v44, 11
	v_and_or_b32 v53, v54, s18, v53
	v_lshl_add_u64 v[54:55], v[8:9], 0, v[172:173]
	global_store_dwordx4 v[54:55], v[50:53], off sc1
	ds_read2_b32 v[54:55], v43 offset0:49 offset1:57
	ds_read2_b32 v[56:57], v43 offset0:16 offset1:24
	ds_read2_b32 v[58:59], v43 offset0:82 offset1:90
	ds_read2_b32 v[60:61], v43 offset0:115 offset1:123
	ds_read2_b32 v[62:63], v43 offset0:148 offset1:156
	ds_read2_b32 v[64:65], v43 offset0:181 offset1:189
	ds_read2_b32 v[66:67], v43 offset0:214 offset1:222
	ds_read2_b32 v[68:69], v43 offset0:247 offset1:255
	s_waitcnt lgkmcnt(7)
	v_bfe_u32 v51, v54, 16, 1
	s_waitcnt lgkmcnt(6)
	v_bfe_u32 v50, v56, 16, 1
	v_add3_u32 v50, v56, v50, s20
	v_lshrrev_b32_e32 v50, 16, v50
	v_add3_u32 v51, v54, v51, s20
	v_and_or_b32 v50, v51, s18, v50
	s_waitcnt lgkmcnt(5)
	v_bfe_u32 v51, v58, 16, 1
	v_add3_u32 v51, v58, v51, s20
	s_waitcnt lgkmcnt(4)
	v_bfe_u32 v52, v60, 16, 1
	v_lshrrev_b32_e32 v51, 16, v51
	v_add3_u32 v52, v60, v52, s20
	v_and_or_b32 v51, v52, s18, v51
	s_waitcnt lgkmcnt(3)
	v_bfe_u32 v52, v62, 16, 1
	v_add3_u32 v52, v62, v52, s20
	s_waitcnt lgkmcnt(2)
	v_bfe_u32 v53, v64, 16, 1
	v_lshrrev_b32_e32 v52, 16, v52
	v_add3_u32 v53, v64, v53, s20
	v_and_or_b32 v52, v53, s18, v52
	s_waitcnt lgkmcnt(1)
	v_bfe_u32 v53, v66, 16, 1
	v_add3_u32 v53, v66, v53, s20
	s_waitcnt lgkmcnt(0)
	v_bfe_u32 v54, v68, 16, 1
	v_lshrrev_b32_e32 v53, 16, v53
	v_add3_u32 v54, v68, v54, s20
	v_add_lshl_u32 v172, s11, v45, 11
	v_and_or_b32 v53, v54, s18, v53
	v_lshl_add_u64 v[70:71], v[8:9], 0, v[172:173]
	global_store_dwordx4 v[70:71], v[50:53], off sc1
	v_bfe_u32 v54, v69, 16, 1
	v_add3_u32 v54, v69, v54, s20
	v_bfe_u32 v50, v57, 16, 1
	v_add3_u32 v50, v57, v50, s20
	v_bfe_u32 v51, v55, 16, 1
	v_lshrrev_b32_e32 v50, 16, v50
	v_add3_u32 v51, v55, v51, s20
	v_and_or_b32 v50, v51, s18, v50
	v_bfe_u32 v51, v59, 16, 1
	v_add3_u32 v51, v59, v51, s20
	v_bfe_u32 v52, v61, 16, 1
	v_lshrrev_b32_e32 v51, 16, v51
	v_add3_u32 v52, v61, v52, s20
	v_and_or_b32 v51, v52, s18, v51
	v_bfe_u32 v52, v63, 16, 1
	v_add3_u32 v52, v63, v52, s20
	v_bfe_u32 v53, v65, 16, 1
	v_lshrrev_b32_e32 v52, 16, v52
	v_add3_u32 v53, v65, v53, s20
	v_and_or_b32 v52, v53, s18, v52
	v_bfe_u32 v53, v67, 16, 1
	v_add3_u32 v53, v67, v53, s20
	v_lshrrev_b32_e32 v53, 16, v53
	v_add_lshl_u32 v172, s11, v46, 11
	v_and_or_b32 v53, v54, s18, v53
	v_lshl_add_u64 v[8:9], v[8:9], 0, v[172:173]
	global_store_dwordx4 v[8:9], v[50:53], off sc1
	s_waitcnt lgkmcnt(0)

; #define LAS __attribute__((address_space(3)))
; template <bool REMAP>
; __device__ __forceinline__ void p0_transpose_item(const float* W, int K, int N, bf16_t* WT, LAS float* scr, int item, int lane) {
;     const int nblk = N / 32, kb = item / nblk, nb = item % nblk, k0 = 64 * kb, n0 = 32 * nb;
;     const int r0 = REMAP ? win_row_of_col(n0) : n0;
; #pragma unroll
;     for (int i = 0; i < 32; ++i) { const int kk = 2 * i + (lane >> 5); scr[kk * 33 + (lane & 31)] = __builtin_nontemporal_load(W + (size_t)(k0 + kk) * N + n0 + (lane & 31)); }
;     asm volatile("s_waitcnt lgkmcnt(0)" ::: "memory");
; __device__ __forceinline__ void transposes_layer(const Args& a, int l, LAS unsigned char* lds, int lane, int wave, int vrot, int nvb) {
;     ...
;     for (int it = vrot * 8 + wave; it < I_IN + I_OUT; it += nvb * 8) {
;         if (it < I_IN) p0_transpose_item<true>(a.in[10] + (size_t)l * D * PO, D, PO, WinT, scr, it, lane);
;         else p0_transpose_item<false>(a.in[15] + (size_t)l * D * D, D, D, WoutT, scr, it - I_IN, lane);
.LBB0_364:
	s_mov_b64 s[0:1], -1
	s_cmpk_gt_i32 s2, 0x67f
	v_add_u32_e32 v55, 0x400, v47
	v_add_u32_e32 v54, 0x400, v48
	v_add_u32_e32 v53, 0x400, v49
	v_add_u32_e32 v52, 0x800, v49
	v_add_u32_e32 v51, 0xc00, v49
	v_add_u32_e32 v50, 0x1000, v49
	s_cbranch_scc0 .LBB0_366
	s_add_i32 s0, s3, 0xffff3000
	s_and_b32 s1, s10, 0x3c0
	s_and_b32 s0, s0, 0x3e0
	s_lshl_b32 s86, s0, 2
	v_or_b32_e32 v56, s1, v10
	v_lshl_add_u64 v[8:9], v[4:5], 0, s[86:87]
	v_lshlrev_b32_e32 v172, 12, v56
	v_lshl_add_u64 v[56:57], v[8:9], 0, v[172:173]
	global_load_dword v58, v[56:57], off nt
	v_or_b32_e32 v56, s1, v11
	v_lshlrev_b32_e32 v172, 12, v56
	v_lshl_add_u64 v[56:57], v[8:9], 0, v[172:173]
	global_load_dword v56, v[56:57], off nt
	s_lshl_b32 s86, s1, 1
	s_waitcnt vmcnt(0)
	ds_write2_b32 v47, v58, v56 offset1:66
	v_or_b32_e32 v56, s1, v12
	v_lshlrev_b32_e32 v172, 12, v56
	v_lshl_add_u64 v[56:57], v[8:9], 0, v[172:173]
	global_load_dword v58, v[56:57], off nt
	v_or_b32_e32 v56, s1, v13
	v_lshlrev_b32_e32 v172, 12, v56
	v_lshl_add_u64 v[56:57], v[8:9], 0, v[172:173]
	global_load_dword v56, v[56:57], off nt
	s_waitcnt vmcnt(0)
	ds_write2_b32 v47, v58, v56 offset0:132 offset1:198
	v_or_b32_e32 v56, s1, v14
	v_lshlrev_b32_e32 v172, 12, v56
	v_lshl_add_u64 v[56:57], v[8:9], 0, v[172:173]
	global_load_dword v58, v[56:57], off nt
	v_or_b32_e32 v56, s1, v15
	v_lshlrev_b32_e32 v172, 12, v56
	v_lshl_add_u64 v[56:57], v[8:9], 0, v[172:173]
	global_load_dword v56, v[56:57], off nt
	s_waitcnt vmcnt(0)
	ds_write2_b32 v55, v58, v56 offset0:8 offset1:74
	v_or_b32_e32 v56, s1, v16
	v_lshlrev_b32_e32 v172, 12, v56
	v_lshl_add_u64 v[56:57], v[8:9], 0, v[172:173]
	global_load_dword v58, v[56:57], off nt
	v_or_b32_e32 v56, s1, v17
	v_lshlrev_b32_e32 v172, 12, v56
	v_lshl_add_u64 v[56:57], v[8:9], 0, v[172:173]
	global_load_dword v56, v[56:57], off nt
	s_waitcnt vmcnt(0)
	ds_write2_b32 v48, v58, v56 offset1:66
	v_or_b32_e32 v56, s1, v18
	v_lshlrev_b32_e32 v172, 12, v56
	v_lshl_add_u64 v[56:57], v[8:9], 0, v[172:173]
	global_load_dword v58, v[56:57], off nt
	v_or_b32_e32 v56, s1, v19
	v_lshlrev_b32_e32 v172, 12, v56
	v_lshl_add_u64 v[56:57], v[8:9], 0, v[172:173]
	global_load_dword v56, v[56:57], off nt
	s_waitcnt vmcnt(0)
	ds_write2_b32 v48, v58, v56 offset0:132 offset1:198
	v_or_b32_e32 v56, s1, v20
	v_lshlrev_b32_e32 v172, 12, v56
	v_lshl_add_u64 v[56:57], v[8:9], 0, v[172:173]
	global_load_dword v58, v[56:57], off nt
	v_or_b32_e32 v56, s1, v21
	v_lshlrev_b32_e32 v172, 12, v56
	v_lshl_add_u64 v[56:57], v[8:9], 0, v[172:173]
	global_load_dword v56, v[56:57], off nt
	s_waitcnt vmcnt(0)
	ds_write2_b32 v54, v58, v56 offset0:8 offset1:74
	v_or_b32_e32 v56, s1, v22
	v_lshlrev_b32_e32 v172, 12, v56
	v_lshl_add_u64 v[56:57], v[8:9], 0, v[172:173]
	global_load_dword v58, v[56:57], off nt
	v_or_b32_e32 v56, s1, v23
	v_lshlrev_b32_e32 v172, 12, v56
	v_lshl_add_u64 v[56:57], v[8:9], 0, v[172:173]
	global_load_dword v56, v[56:57], off nt
	s_waitcnt vmcnt(0)
	ds_write2_b32 v49, v58, v56 offset1:66
	v_or_b32_e32 v56, s1, v24
	v_lshlrev_b32_e32 v172, 12, v56
	v_lshl_add_u64 v[56:57], v[8:9], 0, v[172:173]
	global_load_dword v58, v[56:57], off nt
	v_or_b32_e32 v56, s1, v25
	v_lshlrev_b32_e32 v172, 12, v56
	v_lshl_add_u64 v[56:57], v[8:9], 0, v[172:173]
	global_load_dword v56, v[56:57], off nt
	s_waitcnt vmcnt(0)
	ds_write2_b32 v49, v58, v56 offset0:132 offset1:198
	v_or_b32_e32 v56, s1, v26
	v_lshlrev_b32_e32 v172, 12, v56
	v_lshl_add_u64 v[56:57], v[8:9], 0, v[172:173]
	global_load_dword v58, v[56:57], off nt
	v_or_b32_e32 v56, s1, v27
	v_lshlrev_b32_e32 v172, 12, v56
	v_lshl_add_u64 v[56:57], v[8:9], 0, v[172:173]
	global_load_dword v56, v[56:57], off nt
	s_waitcnt vmcnt(0)
	ds_write2_b32 v53, v58, v56 offset0:8 offset1:74
	v_or_b32_e32 v56, s1, v28
	v_lshlrev_b32_e32 v172, 12, v56
	v_lshl_add_u64 v[56:57], v[8:9], 0, v[172:173]
	global_load_dword v58, v[56:57], off nt
	v_or_b32_e32 v56, s1, v29
	v_lshlrev_b32_e32 v172, 12, v56
	v_lshl_add_u64 v[56:57], v[8:9], 0, v[172:173]
	global_load_dword v56, v[56:57], off nt
	s_waitcnt vmcnt(0)
	ds_write2_b32 v53, v58, v56 offset0:140 offset1:206
	v_or_b32_e32 v56, s1, v30
	v_lshlrev_b32_e32 v172, 12, v56
	v_lshl_add_u64 v[56:57], v[8:9], 0, v[172:173]
	global_load_dword v58, v[56:57], off nt
	v_or_b32_e32 v56, s1, v31
	v_lshlrev_b32_e32 v172, 12, v56
	v_lshl_add_u64 v[56:57], v[8:9], 0, v[172:173]
	global_load_dword v56, v[56:57], off nt
	s_waitcnt vmcnt(0)
	ds_write2_b32 v52, v58, v56 offset0:16 offset1:82
	v_or_b32_e32 v56, s1, v32
	v_lshlrev_b32_e32 v172, 12, v56
	v_lshl_add_u64 v[56:57], v[8:9], 0, v[172:173]
	global_load_dword v58, v[56:57], off nt
	v_or_b32_e32 v56, s1, v33
	v_lshlrev_b32_e32 v172, 12, v56
	v_lshl_add_u64 v[56:57], v[8:9], 0, v[172:173]
	global_load_dword v56, v[56:57], off nt
	s_waitcnt vmcnt(0)
	ds_write2_b32 v52, v58, v56 offset0:148 offset1:214
	v_or_b32_e32 v56, s1, v34
	v_lshlrev_b32_e32 v172, 12, v56
	v_lshl_add_u64 v[56:57], v[8:9], 0, v[172:173]
	global_load_dword v58, v[56:57], off nt
	v_or_b32_e32 v56, s1, v35
	v_lshlrev_b32_e32 v172, 12, v56
	v_lshl_add_u64 v[56:57], v[8:9], 0, v[172:173]
	global_load_dword v56, v[56:57], off nt
	s_waitcnt vmcnt(0)
	ds_write2_b32 v51, v58, v56 offset0:24 offset1:90
	v_or_b32_e32 v56, s1, v36
	v_lshlrev_b32_e32 v172, 12, v56
	v_lshl_add_u64 v[56:57], v[8:9], 0, v[172:173]
	global_load_dword v58, v[56:57], off nt
	v_or_b32_e32 v56, s1, v37
	v_lshlrev_b32_e32 v172, 12, v56
	v_lshl_add_u64 v[56:57], v[8:9], 0, v[172:173]
	global_load_dword v56, v[56:57], off nt
	s_waitcnt vmcnt(0)
; #define LAS __attribute__((address_space(3)))
; __device__ __forceinline__ unsigned pk2(float lo, float hi) { return f2bf_rne(lo) | (f2bf_rne(hi) << 16); }
; template <bool REMAP>
; __device__ __forceinline__ void p0_transpose_item(const float* W, int K, int N, bf16_t* WT, LAS float* scr, int item, int lane) {
;     ...
; #pragma unroll
;     for (int i = 0; i < 32; ++i) { const int kk = 2 * i + (lane >> 5); scr[kk * 33 + (lane & 31)] = __builtin_nontemporal_load(W + (size_t)(k0 + kk) * N + n0 + (lane & 31)); }
;     asm volatile("s_waitcnt lgkmcnt(0)" ::: "memory");
;     const int c = lane & 7;
; #pragma unroll
;     for (int j = 0; j < 4; ++j) { const int n = (lane >> 3) + 8 * j; const LAS float* s = scr + (8 * c) * 33 + n;
;         u32x4 o; o.x = pk2(s[0 * 33], s[1 * 33]); o.y = pk2(s[2 * 33], s[3 * 33]); o.z = pk2(s[4 * 33], s[5 * 33]); o.w = pk2(s[6 * 33], s[7 * 33]);
;         *(u32x4*)(WT + (size_t)(r0 + n) * K + k0 + 8 * c) = o; }
;     asm volatile("s_waitcnt lgkmcnt(0)" ::: "memory");
	ds_write2_b32 v51, v58, v56 offset0:156 offset1:222
	v_or_b32_e32 v56, s1, v38
	v_lshlrev_b32_e32 v172, 12, v56
	v_lshl_add_u64 v[56:57], v[8:9], 0, v[172:173]
	global_load_dword v58, v[56:57], off nt
	v_or_b32_e32 v56, s1, v39
	v_lshlrev_b32_e32 v172, 12, v56
	v_lshl_add_u64 v[56:57], v[8:9], 0, v[172:173]
	global_load_dword v56, v[56:57], off nt
	s_waitcnt vmcnt(0)
	ds_write2_b32 v50, v58, v56 offset0:32 offset1:98
	v_or_b32_e32 v56, s1, v40
	v_lshlrev_b32_e32 v172, 12, v56
	v_lshl_add_u64 v[56:57], v[8:9], 0, v[172:173]
	global_load_dword v56, v[56:57], off nt
	v_or_b32_e32 v57, s1, v41
	v_lshlrev_b32_e32 v172, 12, v57
	v_lshl_add_u64 v[8:9], v[8:9], 0, v[172:173]
	global_load_dword v8, v[8:9], off nt
	s_waitcnt vmcnt(0)
	ds_write2_b32 v50, v56, v8 offset0:164 offset1:230
	s_waitcnt lgkmcnt(0)
	ds_read2_b32 v[60:61], v43 offset0:33 offset1:41
	ds_read2_b32 v[62:63], v43 offset1:8
	ds_read2_b32 v[64:65], v43 offset0:66 offset1:74
	ds_read2_b32 v[66:67], v43 offset0:99 offset1:107
	ds_read2_b32 v[68:69], v43 offset0:132 offset1:140
	ds_read2_b32 v[70:71], v43 offset0:165 offset1:173
	ds_read2_b32 v[72:73], v43 offset0:198 offset1:206
	ds_read2_b32 v[74:75], v43 offset0:231 offset1:239
	s_waitcnt lgkmcnt(7)
	v_bfe_u32 v57, v60, 16, 1
	s_waitcnt lgkmcnt(6)
	v_bfe_u32 v56, v62, 16, 1
	v_add3_u32 v56, v62, v56, s20
	v_lshrrev_b32_e32 v56, 16, v56
	v_add3_u32 v57, v60, v57, s20
	v_and_or_b32 v56, v57, s18, v56
	s_waitcnt lgkmcnt(5)
	v_bfe_u32 v57, v64, 16, 1
	v_add3_u32 v57, v64, v57, s20
	s_waitcnt lgkmcnt(4)
	v_bfe_u32 v58, v66, 16, 1
	v_lshrrev_b32_e32 v57, 16, v57
	v_add3_u32 v58, v66, v58, s20
	v_and_or_b32 v57, v58, s18, v57
	s_waitcnt lgkmcnt(3)
	v_bfe_u32 v58, v68, 16, 1
	v_add3_u32 v58, v68, v58, s20
	s_waitcnt lgkmcnt(2)
	v_bfe_u32 v59, v70, 16, 1
	v_lshrrev_b32_e32 v58, 16, v58
	v_add3_u32 v59, v70, v59, s20
	v_and_or_b32 v58, v59, s18, v58
	s_waitcnt lgkmcnt(1)
	v_bfe_u32 v59, v72, 16, 1
	v_add3_u32 v59, v72, v59, s20
	s_waitcnt lgkmcnt(0)
	v_bfe_u32 v60, v74, 16, 1
	v_lshrrev_b32_e32 v59, 16, v59
	v_add3_u32 v60, v74, v60, s20
	v_and_or_b32 v59, v60, s18, v59
	v_or_b32_e32 v60, s0, v42
	v_lshl_add_u64 v[8:9], v[0:1], 0, s[86:87]
	v_lshlrev_b32_e32 v172, 11, v60
	v_lshl_add_u64 v[76:77], v[8:9], 0, v[172:173]
	global_store_dwordx4 v[76:77], v[56:59], off sc1
	v_bfe_u32 v60, v75, 16, 1
	v_add3_u32 v60, v75, v60, s20
	v_bfe_u32 v56, v63, 16, 1
	v_add3_u32 v56, v63, v56, s20
	v_bfe_u32 v57, v61, 16, 1
	v_lshrrev_b32_e32 v56, 16, v56
	v_add3_u32 v57, v61, v57, s20
	v_and_or_b32 v56, v57, s18, v56
	v_bfe_u32 v57, v65, 16, 1
	v_add3_u32 v57, v65, v57, s20
	v_bfe_u32 v58, v67, 16, 1
	v_lshrrev_b32_e32 v57, 16, v57
	v_add3_u32 v58, v67, v58, s20
	v_and_or_b32 v57, v58, s18, v57
	v_bfe_u32 v58, v69, 16, 1
	v_add3_u32 v58, v69, v58, s20
	v_bfe_u32 v59, v71, 16, 1
	v_lshrrev_b32_e32 v58, 16, v58
	v_add3_u32 v59, v71, v59, s20
	v_and_or_b32 v58, v59, s18, v58
	v_bfe_u32 v59, v73, 16, 1
	v_add3_u32 v59, v73, v59, s20
	v_lshrrev_b32_e32 v59, 16, v59
	v_and_or_b32 v59, v60, s18, v59
	v_or_b32_e32 v60, s0, v44
	v_lshlrev_b32_e32 v172, 11, v60
	v_lshl_add_u64 v[60:61], v[8:9], 0, v[172:173]
	global_store_dwordx4 v[60:61], v[56:59], off sc1
	ds_read2_b32 v[60:61], v43 offset0:49 offset1:57
	ds_read2_b32 v[62:63], v43 offset0:16 offset1:24
	ds_read2_b32 v[64:65], v43 offset0:82 offset1:90
	ds_read2_b32 v[66:67], v43 offset0:115 offset1:123
	ds_read2_b32 v[68:69], v43 offset0:148 offset1:156
	ds_read2_b32 v[70:71], v43 offset0:181 offset1:189
	ds_read2_b32 v[72:73], v43 offset0:214 offset1:222
	ds_read2_b32 v[74:75], v43 offset0:247 offset1:255
	s_waitcnt lgkmcnt(7)
	v_bfe_u32 v57, v60, 16, 1
	s_waitcnt lgkmcnt(6)
	v_bfe_u32 v56, v62, 16, 1
	v_add3_u32 v56, v62, v56, s20
	v_lshrrev_b32_e32 v56, 16, v56
	v_add3_u32 v57, v60, v57, s20
	v_and_or_b32 v56, v57, s18, v56
	s_waitcnt lgkmcnt(5)
	v_bfe_u32 v57, v64, 16, 1
	v_add3_u32 v57, v64, v57, s20
	s_waitcnt lgkmcnt(4)
	v_bfe_u32 v58, v66, 16, 1
	v_lshrrev_b32_e32 v57, 16, v57
	v_add3_u32 v58, v66, v58, s20
	v_and_or_b32 v57, v58, s18, v57
	s_waitcnt lgkmcnt(3)
	v_bfe_u32 v58, v68, 16, 1
	v_add3_u32 v58, v68, v58, s20
	s_waitcnt lgkmcnt(2)
	v_bfe_u32 v59, v70, 16, 1
	v_lshrrev_b32_e32 v58, 16, v58
	v_add3_u32 v59, v70, v59, s20
	v_and_or_b32 v58, v59, s18, v58
	s_waitcnt lgkmcnt(1)
	v_bfe_u32 v59, v72, 16, 1
	v_add3_u32 v59, v72, v59, s20
	s_waitcnt lgkmcnt(0)
	v_bfe_u32 v60, v74, 16, 1
	v_lshrrev_b32_e32 v59, 16, v59
	v_add3_u32 v60, v74, v60, s20
	v_and_or_b32 v59, v60, s18, v59
	v_or_b32_e32 v60, s0, v45
	v_lshlrev_b32_e32 v172, 11, v60
	v_lshl_add_u64 v[76:77], v[8:9], 0, v[172:173]
	global_store_dwordx4 v[76:77], v[56:59], off sc1
	v_bfe_u32 v60, v75, 16, 1
	v_add3_u32 v60, v75, v60, s20
	v_bfe_u32 v56, v63, 16, 1
	v_add3_u32 v56, v63, v56, s20
	v_bfe_u32 v57, v61, 16, 1
	v_lshrrev_b32_e32 v56, 16, v56
	v_add3_u32 v57, v61, v57, s20
	v_and_or_b32 v56, v57, s18, v56
	v_bfe_u32 v57, v65, 16, 1
	v_add3_u32 v57, v65, v57, s20
	v_bfe_u32 v58, v67, 16, 1
	v_lshrrev_b32_e32 v57, 16, v57
	v_add3_u32 v58, v67, v58, s20
	v_and_or_b32 v57, v58, s18, v57
	v_bfe_u32 v58, v69, 16, 1
	v_add3_u32 v58, v69, v58, s20
	v_bfe_u32 v59, v71, 16, 1
	v_lshrrev_b32_e32 v58, 16, v58
	v_add3_u32 v59, v71, v59, s20
	v_and_or_b32 v58, v59, s18, v58
	v_bfe_u32 v59, v73, 16, 1
	v_add3_u32 v59, v73, v59, s20
	v_lshrrev_b32_e32 v59, 16, v59
	v_and_or_b32 v59, v60, s18, v59
	v_or_b32_e32 v60, s0, v46
	v_lshlrev_b32_e32 v172, 11, v60
	v_lshl_add_u64 v[8:9], v[8:9], 0, v[172:173]
	global_store_dwordx4 v[8:9], v[56:59], off sc1
	s_waitcnt lgkmcnt(0)
	s_mov_b64 s[0:1], 0
